# loop-edge edit on 6 GEMM K-loops: loop-carried counter/pointer increments moved in front of the loop-back barrier
# baseline (speedup 1.0000x reference)
; #define PG8_STAGE(bufoff, gbase, voff) do { _Pragma("unroll") for (int _i = 0; _i < 2; ++_i) \
;         __builtin_amdgcn_global_load_lds((const unsigned*)((const char*)(gbase) + (voff)[_i]), (LAS unsigned*)(lds + (bufoff) + ldsw + _i * 8192), 16, 0, 0); } while (0)
; #define PG8_STAGE_A(bufoff, gbase, spf) do { _Pragma("unroll") for (int _i = 0; _i < 2; ++_i) \
;         __builtin_amdgcn_global_load_lds((const unsigned*)((const char*)(gbase) + (Epi::SPECIAL_ROWS && (spf) ? voffS[_i] : voffA[_i])), (LAS unsigned*)(lds + (bufoff) + ldsw + _i * 8192), 16, 0, 0); } while (0)
; #define PG8_LDA(dst, b, h) do { _Pragma("unroll") for (int m = 0; m < 4; ++m) _Pragma("unroll") for (int k = 0; k < 2; ++k) dst[m][k] = *(const LAS bf16x8*)(lds + PG8_SA(b, h) + aoff + m * 2048 + k * 1024); } while (0)
; #define PG8_LDB(dst, b, h) do { _Pragma("unroll") for (int n = 0; n < 2; ++n) _Pragma("unroll") for (int k = 0; k < 2; ++k) dst[n][k] = *(const LAS bf16x8*)(lds + PG8_SB(b, h) + boff + n * 2048 + k * 1024); } while (0)
; #define PG8_MMA(ai, bj, At, Bt) do { __builtin_amdgcn_s_setprio(1); _Pragma("unroll") for (int m = 0; m < 4; ++m) _Pragma("unroll") for (int n = 0; n < 2; ++n) _Pragma("unroll") for (int k = 0; k < 2; ++k) \
;         acc[ai][bj][m][n] = __builtin_amdgcn_mfma_f32_16x16x32_bf16(Bt[n][k], At[m][k], acc[ai][bj][m][n], 0, 0, 0); __builtin_amdgcn_s_setprio(0); } while (0)
; #define PG8_WAIT_V(n) asm volatile("s_waitcnt vmcnt(" #n ")" ::: "memory")
; #define PG8_WAIT_L(n) asm volatile("s_waitcnt lgkmcnt(" #n ")" ::: "memory")
; #define PG8_BAR __builtin_amdgcn_s_barrier()
; #define PG8_SCHED __builtin_amdgcn_sched_barrier(0)
; template <class Epi>
; __device__ __forceinline__ void gemm_phase(LAS unsigned char* lds, const Gemm g, const Sched& S, const Epi& E) {
;     ...
;             PG8_LDB(B0, 0, 0); PG8_LDB(B1, 0, 1); PG8_SCHED; PG8_LDA(At, 0, 0); PG8_STAGE_A(PG8_SA(1, 1), a1 + chA, csp);
;             PG8_WAIT_V(8); PG8_WAIT_L(0); PG8_BAR; PG8_MMA(0, 0, At, B0); PG8_MMA(0, 1, At, B1); PG8_BAR; PG8_SCHED;
;             PG8_LDA(At, 0, 1); PG8_STAGE(PG8_SB(0, 0), b2, voffB); PG8_STAGE(PG8_SB(0, 1), b2 + hstepB, voffB); PG8_STAGE_A(PG8_SA(0, 0), a2, sp2);
;             PG8_WAIT_V(8); PG8_WAIT_L(0); PG8_BAR; PG8_MMA(1, 0, At, B0); PG8_MMA(1, 1, At, B1); PG8_BAR; PG8_SCHED;
.LBB0_45:
	s_add_u32 s0, s12, s40
	s_addc_u32 s1, s13, s41
	s_add_u32 s22, s0, 0x100
	s_addc_u32 s23, s1, 0
	s_add_u32 s30, s72, s40
	s_addc_u32 s31, s73, s41
	s_cmpk_eq_i32 s40, 0x700
	s_cselect_b64 s[0:1], -1, 0
	s_and_b64 s[18:19], s[0:1], exec
	s_cselect_b32 s23, s8, s23
	s_cselect_b32 s22, s9, s22
	s_cselect_b32 s31, s43, s31
	s_cselect_b32 s30, s65, s30
	s_and_b64 s[0:1], s[38:39], s[0:1]
	v_cndmask_b32_e64 v0, v103, v102, s[0:1]
	v_and_b32_e32 v0, 1, v0
	s_add_i32 s18, 0, 0x10000
	v_cmp_eq_u32_e32 vcc, 1, v0
	v_add_u32_e32 v0, s18, v252
	s_add_i32 s19, 0, 0x14000
	ds_read_b128 v[104:107], v0
	ds_read_b128 v[108:111], v0 offset:1024
	ds_read_b128 v[112:115], v0 offset:2048
	ds_read_b128 v[116:119], v0 offset:3072
	v_add_u32_e32 v0, s19, v252
	ds_read_b128 v[120:123], v0
	ds_read_b128 v[124:127], v0 offset:1024
	ds_read_b128 v[162:165], v0 offset:2048
	ds_read_b128 v[166:169], v0 offset:3072
	s_and_b64 s[0:1], s[0:1], exec
	s_cselect_b32 s54, 0, s17
	s_cselect_b32 s55, s2, s16
	v_lshl_add_u64 v[128:129], v[100:101], 0, s[40:41]
	s_add_i32 m0, s47, 0xc000
	ds_read_b128 v[170:173], v249
	ds_read_b128 v[174:177], v249 offset:1024
	ds_read_b128 v[178:181], v249 offset:2048
	ds_read_b128 v[182:185], v249 offset:3072
	ds_read_b128 v[186:189], v249 offset:4096
	ds_read_b128 v[190:193], v249 offset:5120
	ds_read_b128 v[212:215], v249 offset:6144
	ds_read_b128 v[216:219], v249 offset:7168
	global_load_lds_dwordx4 v[128:129], off
	v_lshl_add_u64 v[128:129], v[98:99], 0, s[40:41]
	s_add_i32 m0, s47, 0xe000
	s_nop 0
	global_load_lds_dwordx4 v[128:129], off
	s_waitcnt vmcnt(8)
	s_waitcnt lgkmcnt(0)
	s_barrier
	s_setprio 1
	s_waitcnt lgkmcnt(0)
	v_mfma_f32_16x16x32_bf16 v[158:161], v[104:107], v[170:173], v[158:161]
	v_mfma_f32_16x16x32_bf16 v[154:157], v[112:115], v[170:173], v[154:157]
	v_mfma_f32_16x16x32_bf16 v[142:145], v[104:107], v[178:181], v[142:145]
	v_mfma_f32_16x16x32_bf16 v[138:141], v[112:115], v[178:181], v[138:141]
	v_mfma_f32_16x16x32_bf16 v[86:89], v[104:107], v[186:189], v[86:89]
	v_mfma_f32_16x16x32_bf16 v[82:85], v[112:115], v[186:189], v[82:85]
	v_mfma_f32_16x16x32_bf16 v[94:97], v[104:107], v[212:215], v[94:97]
	v_mfma_f32_16x16x32_bf16 v[90:93], v[112:115], v[212:215], v[90:93]
	v_mfma_f32_16x16x32_bf16 v[158:161], v[108:111], v[174:177], v[158:161]
	v_mfma_f32_16x16x32_bf16 v[154:157], v[116:119], v[174:177], v[154:157]
	v_mfma_f32_16x16x32_bf16 v[142:145], v[108:111], v[182:185], v[142:145]
	v_mfma_f32_16x16x32_bf16 v[138:141], v[116:119], v[182:185], v[138:141]
	v_mfma_f32_16x16x32_bf16 v[86:89], v[108:111], v[190:193], v[86:89]
	v_mfma_f32_16x16x32_bf16 v[82:85], v[116:119], v[190:193], v[82:85]
	v_mfma_f32_16x16x32_bf16 v[94:97], v[108:111], v[216:219], v[94:97]
	v_mfma_f32_16x16x32_bf16 v[90:93], v[116:119], v[216:219], v[90:93]
	s_setprio 0
	s_setprio 1
	v_mfma_f32_16x16x32_bf16 v[150:153], v[120:123], v[170:173], v[150:153]
	v_mfma_f32_16x16x32_bf16 v[146:149], v[162:165], v[170:173], v[146:149]
	v_mfma_f32_16x16x32_bf16 v[134:137], v[120:123], v[178:181], v[134:137]
	v_mfma_f32_16x16x32_bf16 v[128:131], v[162:165], v[178:181], v[130:133]
	v_mfma_f32_16x16x32_bf16 v[62:65], v[120:123], v[186:189], v[62:65]
	v_mfma_f32_16x16x32_bf16 v[58:61], v[162:165], v[186:189], v[58:61]
	v_mfma_f32_16x16x32_bf16 v[78:81], v[120:123], v[212:215], v[78:81]
	v_mfma_f32_16x16x32_bf16 v[74:77], v[162:165], v[212:215], v[74:77]
	v_mfma_f32_16x16x32_bf16 v[150:153], v[124:127], v[174:177], v[150:153]
	v_mfma_f32_16x16x32_bf16 v[146:149], v[166:169], v[174:177], v[146:149]
	v_mfma_f32_16x16x32_bf16 v[134:137], v[124:127], v[182:185], v[134:137]
	v_mfma_f32_16x16x32_bf16 v[128:131], v[166:169], v[182:185], v[128:131]
	v_mfma_f32_16x16x32_bf16 v[62:65], v[124:127], v[190:193], v[62:65]
	v_mfma_f32_16x16x32_bf16 v[58:61], v[166:169], v[190:193], v[58:61]
	v_mfma_f32_16x16x32_bf16 v[78:81], v[124:127], v[216:219], v[78:81]
	v_mfma_f32_16x16x32_bf16 v[74:77], v[166:169], v[216:219], v[74:77]
	s_setprio 0
	s_barrier
	s_add_i32 s0, s18, s46
	v_lshl_add_u64 v[204:205], s[30:31], 0, v[208:209]
	s_mov_b32 m0, s0
	ds_read_b128 v[170:173], v249 offset:16384
	ds_read_b128 v[174:177], v249 offset:17408
	ds_read_b128 v[178:181], v249 offset:18432
	ds_read_b128 v[182:185], v249 offset:19456
	ds_read_b128 v[186:189], v249 offset:20480
	ds_read_b128 v[190:193], v249 offset:21504
	ds_read_b128 v[212:215], v249 offset:22528
	ds_read_b128 v[216:219], v249 offset:23552
	global_load_lds_dwordx4 v[204:205], off
	s_add_i32 m0, s0, 0x2000
	s_add_u32 s0, s30, 0x40000
	v_lshl_add_u64 v[220:221], s[30:31], 0, v[210:211]
	s_addc_u32 s1, s31, 0
	s_add_i32 s18, s19, s46
	global_load_lds_dwordx4 v[220:221], off
	v_lshl_add_u64 v[132:133], s[0:1], 0, v[208:209]
	s_mov_b32 m0, s18
	v_cndmask_b32_e32 v0, v208, v197, vcc
	global_load_lds_dwordx4 v[132:133], off
	v_lshl_add_u64 v[132:133], s[0:1], 0, v[210:211]
	s_add_i32 m0, s18, 0x2000
	v_lshl_add_u64 v[228:229], s[22:23], 0, v[0:1]
	global_load_lds_dwordx4 v[132:133], off
	s_mov_b32 m0, s47
	v_cndmask_b32_e32 v132, v210, v223, vcc
	global_load_lds_dwordx4 v0, s[22:23]
	s_mov_b32 m0, s63
	v_mov_b32_e32 v133, v1
	global_load_lds_dwordx4 v132, s[22:23]
	s_waitcnt vmcnt(8)
	s_waitcnt lgkmcnt(0)
	v_lshl_add_u64 v[230:231], s[22:23], 0, v[132:133]
	s_barrier
; #define PG8_STAGE_A(bufoff, gbase, spf) do { _Pragma("unroll") for (int _i = 0; _i < 2; ++_i) \
;         __builtin_amdgcn_global_load_lds((const unsigned*)((const char*)(gbase) + (Epi::SPECIAL_ROWS && (spf) ? voffS[_i] : voffA[_i])), (LAS unsigned*)(lds + (bufoff) + ldsw + _i * 8192), 16, 0, 0); } while (0)
; #define PG8_LDA(dst, b, h) do { _Pragma("unroll") for (int m = 0; m < 4; ++m) _Pragma("unroll") for (int k = 0; k < 2; ++k) dst[m][k] = *(const LAS bf16x8*)(lds + PG8_SA(b, h) + aoff + m * 2048 + k * 1024); } while (0)
; #define PG8_LDB(dst, b, h) do { _Pragma("unroll") for (int n = 0; n < 2; ++n) _Pragma("unroll") for (int k = 0; k < 2; ++k) dst[n][k] = *(const LAS bf16x8*)(lds + PG8_SB(b, h) + boff + n * 2048 + k * 1024); } while (0)
; #define PG8_MMA(ai, bj, At, Bt) do { __builtin_amdgcn_s_setprio(1); _Pragma("unroll") for (int m = 0; m < 4; ++m) _Pragma("unroll") for (int n = 0; n < 2; ++n) _Pragma("unroll") for (int k = 0; k < 2; ++k) \
;         acc[ai][bj][m][n] = __builtin_amdgcn_mfma_f32_16x16x32_bf16(Bt[n][k], At[m][k], acc[ai][bj][m][n], 0, 0, 0); __builtin_amdgcn_s_setprio(0); } while (0)
; #define PG8_WAIT_V(n) asm volatile("s_waitcnt vmcnt(" #n ")" ::: "memory")
; #define PG8_WAIT_L(n) asm volatile("s_waitcnt lgkmcnt(" #n ")" ::: "memory")
; #define PG8_BAR __builtin_amdgcn_s_barrier()
; #define PG8_SCHED __builtin_amdgcn_sched_barrier(0)
; template <class Epi>
; __device__ __forceinline__ void gemm_phase(LAS unsigned char* lds, const Gemm g, const Sched& S, const Epi& E) {
;     ...
;             PG8_WAIT_V(8); PG8_WAIT_L(0); PG8_BAR; PG8_MMA(1, 0, At, B0); PG8_MMA(1, 1, At, B1); PG8_BAR; PG8_SCHED;
;             PG8_LDB(B0, 1, 0); PG8_LDB(B1, 1, 1); PG8_SCHED; PG8_LDA(At, 1, 0); PG8_STAGE_A(PG8_SA(0, 1), a2 + hA2, sp2);
;             PG8_WAIT_V(8); PG8_WAIT_L(0); PG8_BAR; PG8_MMA(0, 0, At, B0); PG8_MMA(0, 1, At, B1); PG8_BAR; PG8_SCHED;
	s_setprio 1
	s_waitcnt lgkmcnt(0)
	v_mfma_f32_16x16x32_bf16 v[46:49], v[104:107], v[170:173], v[46:49]
	v_mfma_f32_16x16x32_bf16 v[42:45], v[112:115], v[170:173], v[42:45]
	v_mfma_f32_16x16x32_bf16 v[30:33], v[104:107], v[178:181], v[30:33]
	v_mfma_f32_16x16x32_bf16 v[26:29], v[112:115], v[178:181], v[26:29]
	v_mfma_f32_16x16x32_bf16 v[14:17], v[104:107], v[186:189], v[14:17]
	v_mfma_f32_16x16x32_bf16 v[10:13], v[112:115], v[186:189], v[10:13]
	v_mfma_f32_16x16x32_bf16 v[70:73], v[104:107], v[212:215], v[70:73]
	v_mfma_f32_16x16x32_bf16 v[50:53], v[112:115], v[212:215], v[50:53]
	v_mfma_f32_16x16x32_bf16 v[46:49], v[108:111], v[174:177], v[46:49]
	v_mfma_f32_16x16x32_bf16 v[42:45], v[116:119], v[174:177], v[42:45]
	v_mfma_f32_16x16x32_bf16 v[30:33], v[108:111], v[182:185], v[30:33]
	v_mfma_f32_16x16x32_bf16 v[26:29], v[116:119], v[182:185], v[26:29]
	v_mfma_f32_16x16x32_bf16 v[14:17], v[108:111], v[190:193], v[14:17]
	v_mfma_f32_16x16x32_bf16 v[10:13], v[116:119], v[190:193], v[10:13]
	v_mfma_f32_16x16x32_bf16 v[70:73], v[108:111], v[216:219], v[70:73]
	v_mfma_f32_16x16x32_bf16 v[50:53], v[116:119], v[216:219], v[50:53]
	s_setprio 0
	s_setprio 1
	v_mfma_f32_16x16x32_bf16 v[38:41], v[120:123], v[170:173], v[38:41]
	v_mfma_f32_16x16x32_bf16 v[34:37], v[162:165], v[170:173], v[34:37]
	v_mfma_f32_16x16x32_bf16 v[22:25], v[120:123], v[178:181], v[22:25]
	v_mfma_f32_16x16x32_bf16 v[18:21], v[162:165], v[178:181], v[18:21]
	v_mfma_f32_16x16x32_bf16 v[6:9], v[120:123], v[186:189], v[6:9]
	v_mfma_f32_16x16x32_bf16 v[2:5], v[162:165], v[186:189], v[2:5]
	v_mfma_f32_16x16x32_bf16 v[66:69], v[120:123], v[212:215], v[66:69]
	v_mfma_f32_16x16x32_bf16 v[54:57], v[162:165], v[212:215], v[54:57]
	v_mfma_f32_16x16x32_bf16 v[38:41], v[124:127], v[174:177], v[38:41]
	v_mfma_f32_16x16x32_bf16 v[34:37], v[166:169], v[174:177], v[34:37]
	v_mfma_f32_16x16x32_bf16 v[22:25], v[124:127], v[182:185], v[22:25]
	v_mfma_f32_16x16x32_bf16 v[18:21], v[166:169], v[182:185], v[18:21]
	v_mfma_f32_16x16x32_bf16 v[6:9], v[124:127], v[190:193], v[6:9]
	v_mfma_f32_16x16x32_bf16 v[2:5], v[166:169], v[190:193], v[2:5]
	v_mfma_f32_16x16x32_bf16 v[66:69], v[124:127], v[216:219], v[66:69]
	v_mfma_f32_16x16x32_bf16 v[54:57], v[166:169], v[216:219], v[54:57]
	s_setprio 0
	s_barrier
	s_add_i32 s18, 0, 0x18000
	s_add_i32 s19, 0, 0x1c000
	v_add_u32_e32 v116, s18, v252
	v_add_u32_e32 v133, s19, v252
	ds_read_b128 v[104:107], v116
	ds_read_b128 v[108:111], v116 offset:1024
	ds_read_b128 v[112:115], v116 offset:2048
	ds_read_b128 v[116:119], v116 offset:3072
	ds_read_b128 v[120:123], v133
	ds_read_b128 v[124:127], v133 offset:1024
	ds_read_b128 v[162:165], v133 offset:2048
	ds_read_b128 v[166:169], v133 offset:3072
	s_add_u32 s0, s22, s55
	s_addc_u32 s1, s23, s54
	s_mov_b32 m0, s80
	ds_read_b128 v[170:173], v249 offset:32768
	ds_read_b128 v[174:177], v249 offset:33792
	ds_read_b128 v[178:181], v249 offset:34816
	ds_read_b128 v[182:185], v249 offset:35840
	ds_read_b128 v[186:189], v249 offset:36864
	ds_read_b128 v[190:193], v249 offset:37888
	ds_read_b128 v[212:215], v249 offset:38912
	ds_read_b128 v[216:219], v249 offset:39936
	global_load_lds_dwordx4 v0, s[0:1]
	s_mov_b32 m0, s81
	s_nop 0
	global_load_lds_dwordx4 v132, s[0:1]
	s_waitcnt vmcnt(8)
	s_waitcnt lgkmcnt(0)
	s_barrier
	s_setprio 1
	s_waitcnt lgkmcnt(0)
	v_mfma_f32_16x16x32_bf16 v[158:161], v[104:107], v[170:173], v[158:161]
	v_mfma_f32_16x16x32_bf16 v[154:157], v[112:115], v[170:173], v[154:157]
	v_mfma_f32_16x16x32_bf16 v[142:145], v[104:107], v[178:181], v[142:145]
	v_mfma_f32_16x16x32_bf16 v[138:141], v[112:115], v[178:181], v[138:141]
	v_mfma_f32_16x16x32_bf16 v[86:89], v[104:107], v[186:189], v[86:89]
	v_mfma_f32_16x16x32_bf16 v[82:85], v[112:115], v[186:189], v[82:85]
	v_mfma_f32_16x16x32_bf16 v[94:97], v[104:107], v[212:215], v[94:97]
	v_mfma_f32_16x16x32_bf16 v[90:93], v[112:115], v[212:215], v[90:93]
	v_mfma_f32_16x16x32_bf16 v[158:161], v[108:111], v[174:177], v[158:161]
	v_mfma_f32_16x16x32_bf16 v[154:157], v[116:119], v[174:177], v[154:157]
	v_mfma_f32_16x16x32_bf16 v[142:145], v[108:111], v[182:185], v[142:145]
	v_mfma_f32_16x16x32_bf16 v[138:141], v[116:119], v[182:185], v[138:141]
	v_mfma_f32_16x16x32_bf16 v[86:89], v[108:111], v[190:193], v[86:89]
	v_mfma_f32_16x16x32_bf16 v[82:85], v[116:119], v[190:193], v[82:85]
	v_mfma_f32_16x16x32_bf16 v[94:97], v[108:111], v[216:219], v[94:97]
	v_mfma_f32_16x16x32_bf16 v[90:93], v[116:119], v[216:219], v[90:93]
	s_setprio 0
	s_setprio 1
	v_mfma_f32_16x16x32_bf16 v[150:153], v[120:123], v[170:173], v[150:153]
	v_mfma_f32_16x16x32_bf16 v[146:149], v[162:165], v[170:173], v[146:149]
	v_mfma_f32_16x16x32_bf16 v[132:135], v[120:123], v[178:181], v[134:137]
	v_mfma_f32_16x16x32_bf16 v[128:131], v[162:165], v[178:181], v[128:131]
	v_mfma_f32_16x16x32_bf16 v[62:65], v[120:123], v[186:189], v[62:65]
	v_mfma_f32_16x16x32_bf16 v[58:61], v[162:165], v[186:189], v[58:61]
	v_mfma_f32_16x16x32_bf16 v[78:81], v[120:123], v[212:215], v[78:81]
	v_mfma_f32_16x16x32_bf16 v[74:77], v[162:165], v[212:215], v[74:77]
	v_mfma_f32_16x16x32_bf16 v[150:153], v[124:127], v[174:177], v[150:153]
	v_mfma_f32_16x16x32_bf16 v[146:149], v[166:169], v[174:177], v[146:149]
	v_mfma_f32_16x16x32_bf16 v[134:137], v[124:127], v[182:185], v[132:135]
	v_mfma_f32_16x16x32_bf16 v[130:133], v[166:169], v[182:185], v[128:131]
	v_mfma_f32_16x16x32_bf16 v[62:65], v[124:127], v[190:193], v[62:65]
	v_mfma_f32_16x16x32_bf16 v[58:61], v[166:169], v[190:193], v[58:61]
	v_mfma_f32_16x16x32_bf16 v[78:81], v[124:127], v[216:219], v[78:81]
	v_mfma_f32_16x16x32_bf16 v[74:77], v[166:169], v[216:219], v[74:77]
	s_setprio 0
	s_barrier
; #define PG8_STAGE(bufoff, gbase, voff) do { _Pragma("unroll") for (int _i = 0; _i < 2; ++_i) \
;         __builtin_amdgcn_global_load_lds((const unsigned*)((const char*)(gbase) + (voff)[_i]), (LAS unsigned*)(lds + (bufoff) + ldsw + _i * 8192), 16, 0, 0); } while (0)
; #define PG8_STAGE_A(bufoff, gbase, spf) do { _Pragma("unroll") for (int _i = 0; _i < 2; ++_i) \
;         __builtin_amdgcn_global_load_lds((const unsigned*)((const char*)(gbase) + (Epi::SPECIAL_ROWS && (spf) ? voffS[_i] : voffA[_i])), (LAS unsigned*)(lds + (bufoff) + ldsw + _i * 8192), 16, 0, 0); } while (0)
; #define PG8_LDA(dst, b, h) do { _Pragma("unroll") for (int m = 0; m < 4; ++m) _Pragma("unroll") for (int k = 0; k < 2; ++k) dst[m][k] = *(const LAS bf16x8*)(lds + PG8_SA(b, h) + aoff + m * 2048 + k * 1024); } while (0)
; #define PG8_MMA(ai, bj, At, Bt) do { __builtin_amdgcn_s_setprio(1); _Pragma("unroll") for (int m = 0; m < 4; ++m) _Pragma("unroll") for (int n = 0; n < 2; ++n) _Pragma("unroll") for (int k = 0; k < 2; ++k) \
;         acc[ai][bj][m][n] = __builtin_amdgcn_mfma_f32_16x16x32_bf16(Bt[n][k], At[m][k], acc[ai][bj][m][n], 0, 0, 0); __builtin_amdgcn_s_setprio(0); } while (0)
; #define PG8_WAIT_V(n) asm volatile("s_waitcnt vmcnt(" #n ")" ::: "memory")
; #define PG8_WAIT_L(n) asm volatile("s_waitcnt lgkmcnt(" #n ")" ::: "memory")
; #define PG8_BAR __builtin_amdgcn_s_barrier()
; #define PG8_SCHED __builtin_amdgcn_sched_barrier(0)
; template <class Epi>
; __device__ __forceinline__ void gemm_phase(LAS unsigned char* lds, const Gemm g, const Sched& S, const Epi& E) {
;     ...
;             PG8_LDA(At, 1, 1); PG8_STAGE(PG8_SB(1, 0), b3, voffB); PG8_STAGE(PG8_SB(1, 1), b3 + hstepB, voffB); PG8_STAGE_A(PG8_SA(1, 0), a3, sp2);
;             PG8_WAIT_V(8); PG8_WAIT_L(0); PG8_BAR; PG8_MMA(1, 0, At, B0); PG8_MMA(1, 1, At, B1); PG8_BAR; PG8_SCHED;
;         }
	s_add_i32 s0, s18, s46
	v_lshl_add_u64 v[128:129], v[204:205], 0, s[20:21]
	s_mov_b32 m0, s0
	ds_read_b128 v[170:173], v249 offset:49152
	ds_read_b128 v[174:177], v249 offset:50176
	ds_read_b128 v[178:181], v249 offset:51200
	ds_read_b128 v[182:185], v249 offset:52224
	ds_read_b128 v[186:189], v249 offset:53248
	ds_read_b128 v[190:193], v249 offset:54272
	ds_read_b128 v[212:215], v249 offset:55296
	ds_read_b128 v[216:219], v249 offset:56320
	global_load_lds_dwordx4 v[128:129], off
	s_add_i32 m0, s0, 0x2000
	s_add_u32 s0, s30, 0x40080
	v_lshl_add_u64 v[128:129], v[220:221], 0, s[20:21]
	s_addc_u32 s1, s31, 0
	s_add_i32 s18, s19, s46
	global_load_lds_dwordx4 v[128:129], off
	v_lshl_add_u64 v[128:129], s[0:1], 0, v[208:209]
	s_mov_b32 m0, s18
	s_nop 0
	global_load_lds_dwordx4 v[128:129], off
	v_lshl_add_u64 v[128:129], s[0:1], 0, v[210:211]
	s_add_i32 m0, s18, 0x2000
	s_nop 0
	global_load_lds_dwordx4 v[128:129], off
	v_lshl_add_u64 v[128:129], v[228:229], 0, s[20:21]
	s_mov_b32 m0, s84
	s_nop 0
	global_load_lds_dwordx4 v[128:129], off
	v_lshl_add_u64 v[128:129], v[230:231], 0, s[20:21]
	s_mov_b32 m0, s85
	s_nop 0
	global_load_lds_dwordx4 v[128:129], off
	s_waitcnt vmcnt(8)
	s_waitcnt lgkmcnt(0)
	s_barrier
	s_setprio 1
	s_waitcnt lgkmcnt(0)
	v_mfma_f32_16x16x32_bf16 v[46:49], v[104:107], v[170:173], v[46:49]
	v_mfma_f32_16x16x32_bf16 v[42:45], v[112:115], v[170:173], v[42:45]
	v_mfma_f32_16x16x32_bf16 v[30:33], v[104:107], v[178:181], v[30:33]
	v_mfma_f32_16x16x32_bf16 v[26:29], v[112:115], v[178:181], v[26:29]
	v_mfma_f32_16x16x32_bf16 v[14:17], v[104:107], v[186:189], v[14:17]
	v_mfma_f32_16x16x32_bf16 v[10:13], v[112:115], v[186:189], v[10:13]
	v_mfma_f32_16x16x32_bf16 v[70:73], v[104:107], v[212:215], v[70:73]
	v_mfma_f32_16x16x32_bf16 v[50:53], v[112:115], v[212:215], v[50:53]
	v_mfma_f32_16x16x32_bf16 v[46:49], v[108:111], v[174:177], v[46:49]
	v_mfma_f32_16x16x32_bf16 v[42:45], v[116:119], v[174:177], v[42:45]
	v_mfma_f32_16x16x32_bf16 v[30:33], v[108:111], v[182:185], v[30:33]
	v_mfma_f32_16x16x32_bf16 v[26:29], v[116:119], v[182:185], v[26:29]
	v_mfma_f32_16x16x32_bf16 v[14:17], v[108:111], v[190:193], v[14:17]
	v_mfma_f32_16x16x32_bf16 v[10:13], v[116:119], v[190:193], v[10:13]
	v_mfma_f32_16x16x32_bf16 v[70:73], v[108:111], v[216:219], v[70:73]
	v_mfma_f32_16x16x32_bf16 v[50:53], v[116:119], v[216:219], v[50:53]
	s_setprio 0
	s_setprio 1
	v_mfma_f32_16x16x32_bf16 v[38:41], v[120:123], v[170:173], v[38:41]
	v_mfma_f32_16x16x32_bf16 v[34:37], v[162:165], v[170:173], v[34:37]
	v_mfma_f32_16x16x32_bf16 v[22:25], v[120:123], v[178:181], v[22:25]
	v_mfma_f32_16x16x32_bf16 v[18:21], v[162:165], v[178:181], v[18:21]
	v_mfma_f32_16x16x32_bf16 v[6:9], v[120:123], v[186:189], v[6:9]
	v_mfma_f32_16x16x32_bf16 v[2:5], v[162:165], v[186:189], v[2:5]
	v_mfma_f32_16x16x32_bf16 v[66:69], v[120:123], v[212:215], v[66:69]
	v_mfma_f32_16x16x32_bf16 v[54:57], v[162:165], v[212:215], v[54:57]
	v_mfma_f32_16x16x32_bf16 v[38:41], v[124:127], v[174:177], v[38:41]
	v_mfma_f32_16x16x32_bf16 v[34:37], v[166:169], v[174:177], v[34:37]
	v_mfma_f32_16x16x32_bf16 v[22:25], v[124:127], v[182:185], v[22:25]
	v_mfma_f32_16x16x32_bf16 v[18:21], v[166:169], v[182:185], v[18:21]
	v_mfma_f32_16x16x32_bf16 v[6:9], v[124:127], v[190:193], v[6:9]
	v_mfma_f32_16x16x32_bf16 v[2:5], v[166:169], v[190:193], v[2:5]
	v_mfma_f32_16x16x32_bf16 v[66:69], v[124:127], v[216:219], v[66:69]
	v_mfma_f32_16x16x32_bf16 v[54:57], v[166:169], v[216:219], v[54:57]
	s_setprio 0
	s_add_i32 s75, s75, 2
	s_add_u32 s40, s40, 0x100
	s_addc_u32 s41, s41, 0
	s_barrier
	s_cmp_gt_u32 s75, 13
	s_cbranch_scc0 .LBB0_45
	v_readlane_b32 s0, v255, 31
	v_readlane_b32 s1, v255, 32
	s_and_b64 vcc, exec, s[0:1]
	s_cbranch_vccz .LBB0_48
	s_barrier

; #define PG8_STAGE(bufoff, gbase, voff) do { _Pragma("unroll") for (int _i = 0; _i < 2; ++_i) \
;         __builtin_amdgcn_global_load_lds((const unsigned*)((const char*)(gbase) + (voff)[_i]), (LAS unsigned*)(lds + (bufoff) + ldsw + _i * 8192), 16, 0, 0); } while (0)
; #define PG8_STAGE_A(bufoff, gbase, spf) do { _Pragma("unroll") for (int _i = 0; _i < 2; ++_i) \
;         __builtin_amdgcn_global_load_lds((const unsigned*)((const char*)(gbase) + (Epi::SPECIAL_ROWS && (spf) ? voffS[_i] : voffA[_i])), (LAS unsigned*)(lds + (bufoff) + ldsw + _i * 8192), 16, 0, 0); } while (0)
; #define PG8_LDA(dst, b, h) do { _Pragma("unroll") for (int m = 0; m < 4; ++m) _Pragma("unroll") for (int k = 0; k < 2; ++k) dst[m][k] = *(const LAS bf16x8*)(lds + PG8_SA(b, h) + aoff + m * 2048 + k * 1024); } while (0)
; #define PG8_LDB(dst, b, h) do { _Pragma("unroll") for (int n = 0; n < 2; ++n) _Pragma("unroll") for (int k = 0; k < 2; ++k) dst[n][k] = *(const LAS bf16x8*)(lds + PG8_SB(b, h) + boff + n * 2048 + k * 1024); } while (0)
; #define PG8_MMA(ai, bj, At, Bt) do { __builtin_amdgcn_s_setprio(1); _Pragma("unroll") for (int m = 0; m < 4; ++m) _Pragma("unroll") for (int n = 0; n < 2; ++n) _Pragma("unroll") for (int k = 0; k < 2; ++k) \
;         acc[ai][bj][m][n] = __builtin_amdgcn_mfma_f32_16x16x32_bf16(Bt[n][k], At[m][k], acc[ai][bj][m][n], 0, 0, 0); __builtin_amdgcn_s_setprio(0); } while (0)
; #define PG8_WAIT_V(n) asm volatile("s_waitcnt vmcnt(" #n ")" ::: "memory")
; #define PG8_WAIT_L(n) asm volatile("s_waitcnt lgkmcnt(" #n ")" ::: "memory")
; #define PG8_BAR __builtin_amdgcn_s_barrier()
; #define PG8_SCHED __builtin_amdgcn_sched_barrier(0)
; template <class Epi>
; __device__ __forceinline__ void gemm_phase(LAS unsigned char* lds, const Gemm g, const Sched& S, const Epi& E) {
;     ...
;             PG8_LDB(B0, 0, 0); PG8_LDB(B1, 0, 1); PG8_SCHED; PG8_LDA(At, 0, 0); PG8_STAGE_A(PG8_SA(1, 1), a1 + chA, csp);
;             PG8_WAIT_V(8); PG8_WAIT_L(0); PG8_BAR; PG8_MMA(0, 0, At, B0); PG8_MMA(0, 1, At, B1); PG8_BAR; PG8_SCHED;
;             PG8_LDA(At, 0, 1); PG8_STAGE(PG8_SB(0, 0), b2, voffB); PG8_STAGE(PG8_SB(0, 1), b2 + hstepB, voffB); PG8_STAGE_A(PG8_SA(0, 0), a2, sp2);
;             PG8_WAIT_V(8); PG8_WAIT_L(0); PG8_BAR; PG8_MMA(1, 0, At, B0); PG8_MMA(1, 1, At, B1); PG8_BAR; PG8_SCHED;
.LBB0_199:
	s_add_u32 s8, s72, 0xfffc0080
	s_addc_u32 s9, s73, -1
	s_add_i32 s18, 0, 0x10000
	s_cmp_eq_u32 s46, 12
	s_cselect_b32 s9, s2, s9
	s_cselect_b32 s8, s13, s8
	s_cselect_b32 s23, s43, s31
	s_cselect_b32 s22, s65, s30
	s_add_i32 s47, 0, 0x14000
	v_add_u32_e32 v142, s18, v197
	v_add_u32_e32 v158, s47, v197
	ds_read_b128 v[130:133], v142
	ds_read_b128 v[134:137], v142 offset:1024
	ds_read_b128 v[138:141], v142 offset:2048
	ds_read_b128 v[142:145], v142 offset:3072
	ds_read_b128 v[146:149], v158
	ds_read_b128 v[150:153], v158 offset:1024
	ds_read_b128 v[154:157], v158 offset:2048
	ds_read_b128 v[158:161], v158 offset:3072
	v_lshl_add_u64 v[216:217], s[72:73], 0, v[212:213]
	s_add_i32 m0, s80, 0xc000
	ds_read_b128 v[162:165], v204
	ds_read_b128 v[166:169], v204 offset:1024
	ds_read_b128 v[170:173], v204 offset:2048
	ds_read_b128 v[174:177], v204 offset:3072
	ds_read_b128 v[178:181], v204 offset:4096
	ds_read_b128 v[182:185], v204 offset:5120
	ds_read_b128 v[186:189], v204 offset:6144
	ds_read_b128 v[190:193], v204 offset:7168
	global_load_lds_dwordx4 v[216:217], off
	v_lshl_add_u64 v[216:217], s[72:73], 0, v[214:215]
	s_add_i32 m0, s80, 0xe000
	s_nop 0
	global_load_lds_dwordx4 v[216:217], off
	s_waitcnt vmcnt(8)
	s_waitcnt lgkmcnt(0)
	s_barrier
	s_setprio 1
	s_waitcnt lgkmcnt(0)
	v_mfma_f32_16x16x32_bf16 v[126:129], v[130:133], v[162:165], v[126:129]
	v_mfma_f32_16x16x32_bf16 v[122:125], v[138:141], v[162:165], v[122:125]
	v_mfma_f32_16x16x32_bf16 v[110:113], v[130:133], v[170:173], v[110:113]
	v_mfma_f32_16x16x32_bf16 v[106:109], v[138:141], v[170:173], v[106:109]
	v_mfma_f32_16x16x32_bf16 v[94:97], v[130:133], v[178:181], v[94:97]
	v_mfma_f32_16x16x32_bf16 v[90:93], v[138:141], v[178:181], v[90:93]
	v_mfma_f32_16x16x32_bf16 v[78:81], v[130:133], v[186:189], v[78:81]
	v_mfma_f32_16x16x32_bf16 v[74:77], v[138:141], v[186:189], v[74:77]
	v_mfma_f32_16x16x32_bf16 v[126:129], v[134:137], v[166:169], v[126:129]
	v_mfma_f32_16x16x32_bf16 v[122:125], v[142:145], v[166:169], v[122:125]
	v_mfma_f32_16x16x32_bf16 v[110:113], v[134:137], v[174:177], v[110:113]
	v_mfma_f32_16x16x32_bf16 v[106:109], v[142:145], v[174:177], v[106:109]
	v_mfma_f32_16x16x32_bf16 v[94:97], v[134:137], v[182:185], v[94:97]
	v_mfma_f32_16x16x32_bf16 v[90:93], v[142:145], v[182:185], v[90:93]
	v_mfma_f32_16x16x32_bf16 v[78:81], v[134:137], v[190:193], v[78:81]
	v_mfma_f32_16x16x32_bf16 v[74:77], v[142:145], v[190:193], v[74:77]
	s_setprio 0
	s_setprio 1
	v_mfma_f32_16x16x32_bf16 v[118:121], v[146:149], v[162:165], v[118:121]
	v_mfma_f32_16x16x32_bf16 v[114:117], v[154:157], v[162:165], v[114:117]
	v_mfma_f32_16x16x32_bf16 v[102:105], v[146:149], v[170:173], v[102:105]
	v_mfma_f32_16x16x32_bf16 v[98:101], v[154:157], v[170:173], v[98:101]
	v_mfma_f32_16x16x32_bf16 v[86:89], v[146:149], v[178:181], v[86:89]
	v_mfma_f32_16x16x32_bf16 v[82:85], v[154:157], v[178:181], v[82:85]
	v_mfma_f32_16x16x32_bf16 v[70:73], v[146:149], v[186:189], v[70:73]
	v_mfma_f32_16x16x32_bf16 v[66:69], v[154:157], v[186:189], v[66:69]
	v_mfma_f32_16x16x32_bf16 v[118:121], v[150:153], v[166:169], v[118:121]
	v_mfma_f32_16x16x32_bf16 v[114:117], v[158:161], v[166:169], v[114:117]
	v_mfma_f32_16x16x32_bf16 v[102:105], v[150:153], v[174:177], v[102:105]
	v_mfma_f32_16x16x32_bf16 v[98:101], v[158:161], v[174:177], v[98:101]
	v_mfma_f32_16x16x32_bf16 v[86:89], v[150:153], v[182:185], v[86:89]
	v_mfma_f32_16x16x32_bf16 v[82:85], v[158:161], v[182:185], v[82:85]
	v_mfma_f32_16x16x32_bf16 v[70:73], v[150:153], v[190:193], v[70:73]
	v_mfma_f32_16x16x32_bf16 v[66:69], v[158:161], v[190:193], v[66:69]
	s_setprio 0
	s_barrier
	s_add_i32 s18, s18, s36
	v_lshl_add_u64 v[216:217], s[22:23], 0, v[0:1]
	s_mov_b32 m0, s18
	ds_read_b128 v[162:165], v204 offset:16384
	ds_read_b128 v[166:169], v204 offset:17408
	ds_read_b128 v[170:173], v204 offset:18432
	ds_read_b128 v[174:177], v204 offset:19456
	ds_read_b128 v[178:181], v204 offset:20480
	ds_read_b128 v[182:185], v204 offset:21504
	ds_read_b128 v[186:189], v204 offset:22528
	ds_read_b128 v[190:193], v204 offset:23552
	global_load_lds_dwordx4 v[216:217], off
	s_add_i32 m0, s18, 0x2000
	s_add_u32 s18, s22, 0x40000
	v_lshl_add_u64 v[218:219], s[22:23], 0, v[208:209]
	s_addc_u32 s19, s23, 0
	s_add_i32 s47, s47, s36
	global_load_lds_dwordx4 v[218:219], off
	v_lshl_add_u64 v[220:221], s[18:19], 0, v[0:1]
	s_mov_b32 m0, s47
	v_lshl_add_u64 v[222:223], s[8:9], 0, v[208:209]
	global_load_lds_dwordx4 v[220:221], off
	v_lshl_add_u64 v[220:221], s[18:19], 0, v[208:209]
	s_add_i32 m0, s47, 0x2000
	s_nop 0
	global_load_lds_dwordx4 v[220:221], off
	v_lshl_add_u64 v[220:221], s[8:9], 0, v[0:1]
	s_mov_b32 m0, s80
	s_nop 0
	global_load_lds_dwordx4 v[220:221], off
	s_mov_b32 m0, s81
	s_nop 0
	global_load_lds_dwordx4 v[222:223], off
	s_waitcnt vmcnt(8)
	s_waitcnt lgkmcnt(0)
	s_barrier
; #define PG8_STAGE_A(bufoff, gbase, spf) do { _Pragma("unroll") for (int _i = 0; _i < 2; ++_i) \
;         __builtin_amdgcn_global_load_lds((const unsigned*)((const char*)(gbase) + (Epi::SPECIAL_ROWS && (spf) ? voffS[_i] : voffA[_i])), (LAS unsigned*)(lds + (bufoff) + ldsw + _i * 8192), 16, 0, 0); } while (0)
; #define PG8_LDA(dst, b, h) do { _Pragma("unroll") for (int m = 0; m < 4; ++m) _Pragma("unroll") for (int k = 0; k < 2; ++k) dst[m][k] = *(const LAS bf16x8*)(lds + PG8_SA(b, h) + aoff + m * 2048 + k * 1024); } while (0)
; #define PG8_LDB(dst, b, h) do { _Pragma("unroll") for (int n = 0; n < 2; ++n) _Pragma("unroll") for (int k = 0; k < 2; ++k) dst[n][k] = *(const LAS bf16x8*)(lds + PG8_SB(b, h) + boff + n * 2048 + k * 1024); } while (0)
; #define PG8_MMA(ai, bj, At, Bt) do { __builtin_amdgcn_s_setprio(1); _Pragma("unroll") for (int m = 0; m < 4; ++m) _Pragma("unroll") for (int n = 0; n < 2; ++n) _Pragma("unroll") for (int k = 0; k < 2; ++k) \
;         acc[ai][bj][m][n] = __builtin_amdgcn_mfma_f32_16x16x32_bf16(Bt[n][k], At[m][k], acc[ai][bj][m][n], 0, 0, 0); __builtin_amdgcn_s_setprio(0); } while (0)
; #define PG8_WAIT_V(n) asm volatile("s_waitcnt vmcnt(" #n ")" ::: "memory")
; #define PG8_WAIT_L(n) asm volatile("s_waitcnt lgkmcnt(" #n ")" ::: "memory")
; #define PG8_BAR __builtin_amdgcn_s_barrier()
; #define PG8_SCHED __builtin_amdgcn_sched_barrier(0)
; template <class Epi>
; __device__ __forceinline__ void gemm_phase(LAS unsigned char* lds, const Gemm g, const Sched& S, const Epi& E) {
;     ...
;             PG8_WAIT_V(8); PG8_WAIT_L(0); PG8_BAR; PG8_MMA(1, 0, At, B0); PG8_MMA(1, 1, At, B1); PG8_BAR; PG8_SCHED;
;             PG8_LDB(B0, 1, 0); PG8_LDB(B1, 1, 1); PG8_SCHED; PG8_LDA(At, 1, 0); PG8_STAGE_A(PG8_SA(0, 1), a2 + hA2, sp2);
;             PG8_WAIT_V(8); PG8_WAIT_L(0); PG8_BAR; PG8_MMA(0, 0, At, B0); PG8_MMA(0, 1, At, B1); PG8_BAR; PG8_SCHED;
	s_setprio 1
	s_waitcnt lgkmcnt(0)
	v_mfma_f32_16x16x32_bf16 v[62:65], v[130:133], v[162:165], v[62:65]
	v_mfma_f32_16x16x32_bf16 v[58:61], v[138:141], v[162:165], v[58:61]
	v_mfma_f32_16x16x32_bf16 v[46:49], v[130:133], v[170:173], v[46:49]
	v_mfma_f32_16x16x32_bf16 v[42:45], v[138:141], v[170:173], v[42:45]
	v_mfma_f32_16x16x32_bf16 v[30:33], v[130:133], v[178:181], v[30:33]
	v_mfma_f32_16x16x32_bf16 v[26:29], v[138:141], v[178:181], v[26:29]
	v_mfma_f32_16x16x32_bf16 v[14:17], v[130:133], v[186:189], v[14:17]
	v_mfma_f32_16x16x32_bf16 v[10:13], v[138:141], v[186:189], v[10:13]
	v_mfma_f32_16x16x32_bf16 v[62:65], v[134:137], v[166:169], v[62:65]
	v_mfma_f32_16x16x32_bf16 v[58:61], v[142:145], v[166:169], v[58:61]
	v_mfma_f32_16x16x32_bf16 v[46:49], v[134:137], v[174:177], v[46:49]
	v_mfma_f32_16x16x32_bf16 v[42:45], v[142:145], v[174:177], v[42:45]
	v_mfma_f32_16x16x32_bf16 v[30:33], v[134:137], v[182:185], v[30:33]
	v_mfma_f32_16x16x32_bf16 v[26:29], v[142:145], v[182:185], v[26:29]
	v_mfma_f32_16x16x32_bf16 v[14:17], v[134:137], v[190:193], v[14:17]
	v_mfma_f32_16x16x32_bf16 v[10:13], v[142:145], v[190:193], v[10:13]
	s_setprio 0
	s_setprio 1
	v_mfma_f32_16x16x32_bf16 v[54:57], v[146:149], v[162:165], v[54:57]
	v_mfma_f32_16x16x32_bf16 v[50:53], v[154:157], v[162:165], v[50:53]
	v_mfma_f32_16x16x32_bf16 v[38:41], v[146:149], v[170:173], v[38:41]
	v_mfma_f32_16x16x32_bf16 v[34:37], v[154:157], v[170:173], v[34:37]
	v_mfma_f32_16x16x32_bf16 v[22:25], v[146:149], v[178:181], v[22:25]
	v_mfma_f32_16x16x32_bf16 v[18:21], v[154:157], v[178:181], v[18:21]
	v_mfma_f32_16x16x32_bf16 v[6:9], v[146:149], v[186:189], v[6:9]
	v_mfma_f32_16x16x32_bf16 v[2:5], v[154:157], v[186:189], v[2:5]
	v_mfma_f32_16x16x32_bf16 v[54:57], v[150:153], v[166:169], v[54:57]
	v_mfma_f32_16x16x32_bf16 v[50:53], v[158:161], v[166:169], v[50:53]
	v_mfma_f32_16x16x32_bf16 v[38:41], v[150:153], v[174:177], v[38:41]
	v_mfma_f32_16x16x32_bf16 v[34:37], v[158:161], v[174:177], v[34:37]
	v_mfma_f32_16x16x32_bf16 v[22:25], v[150:153], v[182:185], v[22:25]
	v_mfma_f32_16x16x32_bf16 v[18:21], v[158:161], v[182:185], v[18:21]
	v_mfma_f32_16x16x32_bf16 v[6:9], v[150:153], v[190:193], v[6:9]
	v_mfma_f32_16x16x32_bf16 v[2:5], v[158:161], v[190:193], v[2:5]
	s_setprio 0
	s_barrier
	s_add_i32 s18, 0, 0x18000
	s_add_i32 s19, 0, 0x1c000
	v_add_u32_e32 v142, s18, v197
	v_add_u32_e32 v158, s19, v197
	ds_read_b128 v[130:133], v142
	ds_read_b128 v[134:137], v142 offset:1024
	ds_read_b128 v[138:141], v142 offset:2048
	ds_read_b128 v[142:145], v142 offset:3072
	ds_read_b128 v[146:149], v158
	ds_read_b128 v[150:153], v158 offset:1024
	ds_read_b128 v[154:157], v158 offset:2048
	ds_read_b128 v[158:161], v158 offset:3072
	s_add_u32 s8, s8, 0x40000
	s_addc_u32 s9, s9, 0
	s_mov_b32 m0, s82
	v_lshl_add_u64 v[224:225], s[8:9], 0, v[0:1]
	ds_read_b128 v[162:165], v204 offset:32768
	ds_read_b128 v[166:169], v204 offset:33792
	ds_read_b128 v[170:173], v204 offset:34816
	ds_read_b128 v[174:177], v204 offset:35840
	ds_read_b128 v[178:181], v204 offset:36864
	ds_read_b128 v[182:185], v204 offset:37888
	ds_read_b128 v[186:189], v204 offset:38912
	ds_read_b128 v[190:193], v204 offset:39936
	global_load_lds_dwordx4 v[224:225], off
	v_lshl_add_u64 v[224:225], s[8:9], 0, v[208:209]
	s_mov_b32 m0, s83
	s_nop 0
	global_load_lds_dwordx4 v[224:225], off
	s_waitcnt vmcnt(8)
	s_waitcnt lgkmcnt(0)
	s_barrier
	s_setprio 1
	s_waitcnt lgkmcnt(0)
	v_mfma_f32_16x16x32_bf16 v[126:129], v[130:133], v[162:165], v[126:129]
	v_mfma_f32_16x16x32_bf16 v[122:125], v[138:141], v[162:165], v[122:125]
	v_mfma_f32_16x16x32_bf16 v[110:113], v[130:133], v[170:173], v[110:113]
	v_mfma_f32_16x16x32_bf16 v[106:109], v[138:141], v[170:173], v[106:109]
	v_mfma_f32_16x16x32_bf16 v[94:97], v[130:133], v[178:181], v[94:97]
	v_mfma_f32_16x16x32_bf16 v[90:93], v[138:141], v[178:181], v[90:93]
	v_mfma_f32_16x16x32_bf16 v[78:81], v[130:133], v[186:189], v[78:81]
	v_mfma_f32_16x16x32_bf16 v[74:77], v[138:141], v[186:189], v[74:77]
	v_mfma_f32_16x16x32_bf16 v[126:129], v[134:137], v[166:169], v[126:129]
	v_mfma_f32_16x16x32_bf16 v[122:125], v[142:145], v[166:169], v[122:125]
	v_mfma_f32_16x16x32_bf16 v[110:113], v[134:137], v[174:177], v[110:113]
	v_mfma_f32_16x16x32_bf16 v[106:109], v[142:145], v[174:177], v[106:109]
	v_mfma_f32_16x16x32_bf16 v[94:97], v[134:137], v[182:185], v[94:97]
	v_mfma_f32_16x16x32_bf16 v[90:93], v[142:145], v[182:185], v[90:93]
	v_mfma_f32_16x16x32_bf16 v[78:81], v[134:137], v[190:193], v[78:81]
	v_mfma_f32_16x16x32_bf16 v[74:77], v[142:145], v[190:193], v[74:77]
	s_setprio 0
	s_setprio 1
	v_mfma_f32_16x16x32_bf16 v[118:121], v[146:149], v[162:165], v[118:121]
	v_mfma_f32_16x16x32_bf16 v[114:117], v[154:157], v[162:165], v[114:117]
	v_mfma_f32_16x16x32_bf16 v[102:105], v[146:149], v[170:173], v[102:105]
	v_mfma_f32_16x16x32_bf16 v[98:101], v[154:157], v[170:173], v[98:101]
	v_mfma_f32_16x16x32_bf16 v[86:89], v[146:149], v[178:181], v[86:89]
	v_mfma_f32_16x16x32_bf16 v[82:85], v[154:157], v[178:181], v[82:85]
	v_mfma_f32_16x16x32_bf16 v[70:73], v[146:149], v[186:189], v[70:73]
	v_mfma_f32_16x16x32_bf16 v[66:69], v[154:157], v[186:189], v[66:69]
	v_mfma_f32_16x16x32_bf16 v[118:121], v[150:153], v[166:169], v[118:121]
	v_mfma_f32_16x16x32_bf16 v[114:117], v[158:161], v[166:169], v[114:117]
	v_mfma_f32_16x16x32_bf16 v[102:105], v[150:153], v[174:177], v[102:105]
	v_mfma_f32_16x16x32_bf16 v[98:101], v[158:161], v[174:177], v[98:101]
	v_mfma_f32_16x16x32_bf16 v[86:89], v[150:153], v[182:185], v[86:89]
	v_mfma_f32_16x16x32_bf16 v[82:85], v[158:161], v[182:185], v[82:85]
	v_mfma_f32_16x16x32_bf16 v[70:73], v[150:153], v[190:193], v[70:73]
	v_mfma_f32_16x16x32_bf16 v[66:69], v[158:161], v[190:193], v[66:69]
	s_setprio 0
	s_barrier
; #define PG8_STAGE(bufoff, gbase, voff) do { _Pragma("unroll") for (int _i = 0; _i < 2; ++_i) \
;         __builtin_amdgcn_global_load_lds((const unsigned*)((const char*)(gbase) + (voff)[_i]), (LAS unsigned*)(lds + (bufoff) + ldsw + _i * 8192), 16, 0, 0); } while (0)
; #define PG8_STAGE_A(bufoff, gbase, spf) do { _Pragma("unroll") for (int _i = 0; _i < 2; ++_i) \
;         __builtin_amdgcn_global_load_lds((const unsigned*)((const char*)(gbase) + (Epi::SPECIAL_ROWS && (spf) ? voffS[_i] : voffA[_i])), (LAS unsigned*)(lds + (bufoff) + ldsw + _i * 8192), 16, 0, 0); } while (0)
; #define PG8_WAIT_V(n) asm volatile("s_waitcnt vmcnt(" #n ")" ::: "memory")
; #define PG8_WAIT_L(n) asm volatile("s_waitcnt lgkmcnt(" #n ")" ::: "memory")
; template <class Epi>
; __device__ __forceinline__ void gemm_phase(LAS unsigned char* lds, const Gemm g, const Sched& S, const Epi& E) {
;     ...
;         for (int t = 0; t < nt; t += 2) {
;             const bool last = (t == nt - 2);
;             const char* a1 = cA + (size_t)((t + 1) & kmask) * kstep;
;             const char* a2 = last ? nA : cA + (size_t)((t + 2) & kmask) * kstep; const char* b2 = last ? nB : cB + (size_t)((t + 2) & kmask) * kstep;
;             const char* a3 = a2 + kstep; const char* b3 = b2 + kstep;
;             const bool sp2 = last ? nsp : csp; const size_t hA2 = last ? nhA : chA;
;             PG8_LDB(B0, 0, 0); PG8_LDB(B1, 0, 1); PG8_SCHED; PG8_LDA(At, 0, 0); PG8_STAGE_A(PG8_SA(1, 1), a1 + chA, csp);
;             PG8_WAIT_V(8); PG8_WAIT_L(0); PG8_BAR; PG8_MMA(0, 0, At, B0); PG8_MMA(0, 1, At, B1); PG8_BAR; PG8_SCHED;
;             PG8_LDA(At, 0, 1); PG8_STAGE(PG8_SB(0, 0), b2, voffB); PG8_STAGE(PG8_SB(0, 1), b2 + hstepB, voffB); PG8_STAGE_A(PG8_SA(0, 0), a2, sp2);
;             PG8_WAIT_V(8); PG8_WAIT_L(0); PG8_BAR; PG8_MMA(1, 0, At, B0); PG8_MMA(1, 1, At, B1); PG8_BAR; PG8_SCHED;
;             PG8_LDB(B0, 1, 0); PG8_LDB(B1, 1, 1); PG8_SCHED; PG8_LDA(At, 1, 0); PG8_STAGE_A(PG8_SA(0, 1), a2 + hA2, sp2);
;             PG8_WAIT_V(8); PG8_WAIT_L(0); PG8_BAR; PG8_MMA(0, 0, At, B0); PG8_MMA(0, 1, At, B1); PG8_BAR; PG8_SCHED;
;             PG8_LDA(At, 1, 1); PG8_STAGE(PG8_SB(1, 0), b3, voffB); PG8_STAGE(PG8_SB(1, 1), b3 + hstepB, voffB); PG8_STAGE_A(PG8_SA(1, 0), a3, sp2);
;             PG8_WAIT_V(8); PG8_WAIT_L(0); PG8_BAR; PG8_MMA(1, 0, At, B0); PG8_MMA(1, 1, At, B1); PG8_BAR; PG8_SCHED;
	s_add_i32 s8, s18, s36
	v_lshl_add_u64 v[216:217], v[216:217], 0, s[20:21]
	s_mov_b32 m0, s8
	ds_read_b128 v[162:165], v204 offset:49152
	ds_read_b128 v[166:169], v204 offset:50176
	ds_read_b128 v[170:173], v204 offset:51200
	ds_read_b128 v[174:177], v204 offset:52224
	ds_read_b128 v[178:181], v204 offset:53248
	ds_read_b128 v[182:185], v204 offset:54272
	ds_read_b128 v[186:189], v204 offset:55296
	ds_read_b128 v[190:193], v204 offset:56320
	global_load_lds_dwordx4 v[216:217], off
	s_add_i32 m0, s8, 0x2000
	s_add_u32 s8, s22, 0x40080
	v_lshl_add_u64 v[216:217], v[218:219], 0, s[20:21]
	s_addc_u32 s9, s23, 0
	s_add_i32 s18, s19, s36
	global_load_lds_dwordx4 v[216:217], off
	v_lshl_add_u64 v[216:217], s[8:9], 0, v[0:1]
	s_mov_b32 m0, s18
	s_nop 0
	global_load_lds_dwordx4 v[216:217], off
	v_lshl_add_u64 v[216:217], s[8:9], 0, v[208:209]
	s_add_i32 m0, s18, 0x2000
	s_nop 0
	global_load_lds_dwordx4 v[216:217], off
	v_lshl_add_u64 v[216:217], v[220:221], 0, s[20:21]
	s_mov_b32 m0, s85
	s_nop 0
	global_load_lds_dwordx4 v[216:217], off
	v_lshl_add_u64 v[216:217], v[222:223], 0, s[20:21]
	s_mov_b32 m0, s86
	s_nop 0
	global_load_lds_dwordx4 v[216:217], off
	s_waitcnt vmcnt(8)
	s_waitcnt lgkmcnt(0)
	s_barrier
	s_setprio 1
	s_waitcnt lgkmcnt(0)
	v_mfma_f32_16x16x32_bf16 v[62:65], v[130:133], v[162:165], v[62:65]
	v_mfma_f32_16x16x32_bf16 v[58:61], v[138:141], v[162:165], v[58:61]
	v_mfma_f32_16x16x32_bf16 v[46:49], v[130:133], v[170:173], v[46:49]
	v_mfma_f32_16x16x32_bf16 v[42:45], v[138:141], v[170:173], v[42:45]
	v_mfma_f32_16x16x32_bf16 v[30:33], v[130:133], v[178:181], v[30:33]
	v_mfma_f32_16x16x32_bf16 v[26:29], v[138:141], v[178:181], v[26:29]
	v_mfma_f32_16x16x32_bf16 v[14:17], v[130:133], v[186:189], v[14:17]
	v_mfma_f32_16x16x32_bf16 v[10:13], v[138:141], v[186:189], v[10:13]
	v_mfma_f32_16x16x32_bf16 v[62:65], v[134:137], v[166:169], v[62:65]
	v_mfma_f32_16x16x32_bf16 v[58:61], v[142:145], v[166:169], v[58:61]
	v_mfma_f32_16x16x32_bf16 v[46:49], v[134:137], v[174:177], v[46:49]
	v_mfma_f32_16x16x32_bf16 v[42:45], v[142:145], v[174:177], v[42:45]
	v_mfma_f32_16x16x32_bf16 v[30:33], v[134:137], v[182:185], v[30:33]
	v_mfma_f32_16x16x32_bf16 v[26:29], v[142:145], v[182:185], v[26:29]
	v_mfma_f32_16x16x32_bf16 v[14:17], v[134:137], v[190:193], v[14:17]
	v_mfma_f32_16x16x32_bf16 v[10:13], v[142:145], v[190:193], v[10:13]
	s_setprio 0
	s_setprio 1
	v_mfma_f32_16x16x32_bf16 v[54:57], v[146:149], v[162:165], v[54:57]
	v_mfma_f32_16x16x32_bf16 v[50:53], v[154:157], v[162:165], v[50:53]
	v_mfma_f32_16x16x32_bf16 v[38:41], v[146:149], v[170:173], v[38:41]
	v_mfma_f32_16x16x32_bf16 v[34:37], v[154:157], v[170:173], v[34:37]
	v_mfma_f32_16x16x32_bf16 v[22:25], v[146:149], v[178:181], v[22:25]
	v_mfma_f32_16x16x32_bf16 v[18:21], v[154:157], v[178:181], v[18:21]
	v_mfma_f32_16x16x32_bf16 v[6:9], v[146:149], v[186:189], v[6:9]
	v_mfma_f32_16x16x32_bf16 v[2:5], v[154:157], v[186:189], v[2:5]
	v_mfma_f32_16x16x32_bf16 v[54:57], v[150:153], v[166:169], v[54:57]
	v_mfma_f32_16x16x32_bf16 v[50:53], v[158:161], v[166:169], v[50:53]
	v_mfma_f32_16x16x32_bf16 v[38:41], v[150:153], v[174:177], v[38:41]
	v_mfma_f32_16x16x32_bf16 v[34:37], v[158:161], v[174:177], v[34:37]
	v_mfma_f32_16x16x32_bf16 v[22:25], v[150:153], v[182:185], v[22:25]
	v_mfma_f32_16x16x32_bf16 v[18:21], v[158:161], v[182:185], v[18:21]
	v_mfma_f32_16x16x32_bf16 v[6:9], v[150:153], v[190:193], v[6:9]
	v_mfma_f32_16x16x32_bf16 v[2:5], v[158:161], v[190:193], v[2:5]
	s_setprio 0
	s_add_i32 s46, s46, 2
	s_add_u32 s72, s72, 0x100
	s_addc_u32 s73, s73, 0
	s_add_u32 s30, s30, 0x100
	s_addc_u32 s31, s31, 0
	s_barrier
	s_cmp_gt_u32 s46, 13
	s_cbranch_scc0 .LBB0_199
	s_and_b64 vcc, exec, s[16:17]
	s_cbranch_vccz .LBB0_202
	s_barrier

; #define PG8_STAGE(bufoff, gbase, voff) do { _Pragma("unroll") for (int _i = 0; _i < 2; ++_i) \
;         __builtin_amdgcn_global_load_lds((const unsigned*)((const char*)(gbase) + (voff)[_i]), (LAS unsigned*)(lds + (bufoff) + ldsw + _i * 8192), 16, 0, 0); } while (0)
; #define PG8_STAGE_A(bufoff, gbase, spf) do { _Pragma("unroll") for (int _i = 0; _i < 2; ++_i) \
;         __builtin_amdgcn_global_load_lds((const unsigned*)((const char*)(gbase) + (Epi::SPECIAL_ROWS && (spf) ? voffS[_i] : voffA[_i])), (LAS unsigned*)(lds + (bufoff) + ldsw + _i * 8192), 16, 0, 0); } while (0)
; #define PG8_LDA(dst, b, h) do { _Pragma("unroll") for (int m = 0; m < 4; ++m) _Pragma("unroll") for (int k = 0; k < 2; ++k) dst[m][k] = *(const LAS bf16x8*)(lds + PG8_SA(b, h) + aoff + m * 2048 + k * 1024); } while (0)
; #define PG8_LDB(dst, b, h) do { _Pragma("unroll") for (int n = 0; n < 2; ++n) _Pragma("unroll") for (int k = 0; k < 2; ++k) dst[n][k] = *(const LAS bf16x8*)(lds + PG8_SB(b, h) + boff + n * 2048 + k * 1024); } while (0)
; #define PG8_WAIT_V(n) asm volatile("s_waitcnt vmcnt(" #n ")" ::: "memory")
; #define PG8_WAIT_L(n) asm volatile("s_waitcnt lgkmcnt(" #n ")" ::: "memory")
; #define PG8_BAR __builtin_amdgcn_s_barrier()
; #define PG8_SCHED __builtin_amdgcn_sched_barrier(0)
; template <class Epi>
; __device__ __forceinline__ void gemm_phase(LAS unsigned char* lds, const Gemm g, const Sched& S, const Epi& E) {
;     ...
;             const char* a1 = cA + (size_t)((t + 1) & kmask) * kstep;
;             const char* a2 = last ? nA : cA + (size_t)((t + 2) & kmask) * kstep; const char* b2 = last ? nB : cB + (size_t)((t + 2) & kmask) * kstep;
;             const char* a3 = a2 + kstep; const char* b3 = b2 + kstep;
;             const bool sp2 = last ? nsp : csp; const size_t hA2 = last ? nhA : chA;
;             PG8_LDB(B0, 0, 0); PG8_LDB(B1, 0, 1); PG8_SCHED; PG8_LDA(At, 0, 0); PG8_STAGE_A(PG8_SA(1, 1), a1 + chA, csp);
;             PG8_WAIT_V(8); PG8_WAIT_L(0); PG8_BAR; PG8_MMA(0, 0, At, B0); PG8_MMA(0, 1, At, B1); PG8_BAR; PG8_SCHED;
;             PG8_LDA(At, 0, 1); PG8_STAGE(PG8_SB(0, 0), b2, voffB); PG8_STAGE(PG8_SB(0, 1), b2 + hstepB, voffB); PG8_STAGE_A(PG8_SA(0, 0), a2, sp2);
;             PG8_WAIT_V(8); PG8_WAIT_L(0); PG8_BAR; PG8_MMA(1, 0, At, B0); PG8_MMA(1, 1, At, B1); PG8_BAR; PG8_SCHED;
.LBB0_332:
	s_add_u32 s8, s12, 0xfffc0080
	s_addc_u32 s9, s13, -1
	s_add_i32 s18, 0, 0x10000
	s_cmp_eq_u32 s81, 12
	s_cselect_b32 s9, s1, s9
	s_cselect_b32 s8, s35, s8
	v_add_u32_e32 v152, s18, v154
	s_cselect_b32 s23, s17, s31
	s_cselect_b32 s22, s80, s30
	s_add_i32 s54, 0, 0x14000
	ds_read_b128 v[140:143], v152
	ds_read_b128 v[144:147], v152 offset:1024
	ds_read_b128 v[148:151], v152 offset:2048
	ds_read_b128 v[156:159], v152 offset:3072
	v_add_u32_e32 v152, s54, v154
	ds_read_b128 v[160:163], v152
	ds_read_b128 v[164:167], v152 offset:1024
	ds_read_b128 v[168:171], v152 offset:2048
	ds_read_b128 v[172:175], v152 offset:3072
	v_lshl_add_u64 v[152:153], s[12:13], 0, v[136:137]
	s_add_i32 m0, s63, 0xc000
	ds_read_b128 v[176:179], v155
	ds_read_b128 v[180:183], v155 offset:1024
	ds_read_b128 v[184:187], v155 offset:2048
	ds_read_b128 v[188:191], v155 offset:3072
	ds_read_b128 v[208:211], v155 offset:4096
	ds_read_b128 v[212:215], v155 offset:5120
	ds_read_b128 v[216:219], v155 offset:6144
	ds_read_b128 v[220:223], v155 offset:7168
	global_load_lds_dwordx4 v[152:153], off
	v_lshl_add_u64 v[152:153], s[12:13], 0, v[138:139]
	s_add_i32 m0, s63, 0xe000
	s_nop 0
	global_load_lds_dwordx4 v[152:153], off
	s_waitcnt vmcnt(8)
	s_waitcnt lgkmcnt(0)
	s_barrier
	s_setprio 1
	s_waitcnt lgkmcnt(0)
	v_mfma_f32_16x16x32_bf16 v[126:129], v[140:143], v[176:179], v[126:129]
	v_mfma_f32_16x16x32_bf16 v[122:125], v[148:151], v[176:179], v[122:125]
	v_mfma_f32_16x16x32_bf16 v[110:113], v[140:143], v[184:187], v[110:113]
	v_mfma_f32_16x16x32_bf16 v[106:109], v[148:151], v[184:187], v[106:109]
	v_mfma_f32_16x16x32_bf16 v[94:97], v[140:143], v[208:211], v[94:97]
	v_mfma_f32_16x16x32_bf16 v[90:93], v[148:151], v[208:211], v[90:93]
	v_mfma_f32_16x16x32_bf16 v[78:81], v[140:143], v[216:219], v[78:81]
	v_mfma_f32_16x16x32_bf16 v[74:77], v[148:151], v[216:219], v[74:77]
	v_mfma_f32_16x16x32_bf16 v[126:129], v[144:147], v[180:183], v[126:129]
	v_mfma_f32_16x16x32_bf16 v[122:125], v[156:159], v[180:183], v[122:125]
	v_mfma_f32_16x16x32_bf16 v[110:113], v[144:147], v[188:191], v[110:113]
	v_mfma_f32_16x16x32_bf16 v[106:109], v[156:159], v[188:191], v[106:109]
	v_mfma_f32_16x16x32_bf16 v[94:97], v[144:147], v[212:215], v[94:97]
	v_mfma_f32_16x16x32_bf16 v[90:93], v[156:159], v[212:215], v[90:93]
	v_mfma_f32_16x16x32_bf16 v[78:81], v[144:147], v[220:223], v[78:81]
	v_mfma_f32_16x16x32_bf16 v[74:77], v[156:159], v[220:223], v[74:77]
	s_setprio 0
	s_setprio 1
	v_mfma_f32_16x16x32_bf16 v[118:121], v[160:163], v[176:179], v[118:121]
	v_mfma_f32_16x16x32_bf16 v[114:117], v[168:171], v[176:179], v[114:117]
	v_mfma_f32_16x16x32_bf16 v[102:105], v[160:163], v[184:187], v[102:105]
	v_mfma_f32_16x16x32_bf16 v[98:101], v[168:171], v[184:187], v[98:101]
	v_mfma_f32_16x16x32_bf16 v[86:89], v[160:163], v[208:211], v[86:89]
	v_mfma_f32_16x16x32_bf16 v[82:85], v[168:171], v[208:211], v[82:85]
	v_mfma_f32_16x16x32_bf16 v[70:73], v[160:163], v[216:219], v[70:73]
	v_mfma_f32_16x16x32_bf16 v[66:69], v[168:171], v[216:219], v[66:69]
	v_mfma_f32_16x16x32_bf16 v[118:121], v[164:167], v[180:183], v[118:121]
	v_mfma_f32_16x16x32_bf16 v[114:117], v[172:175], v[180:183], v[114:117]
	v_mfma_f32_16x16x32_bf16 v[102:105], v[164:167], v[188:191], v[102:105]
	v_mfma_f32_16x16x32_bf16 v[98:101], v[172:175], v[188:191], v[98:101]
	v_mfma_f32_16x16x32_bf16 v[86:89], v[164:167], v[212:215], v[86:89]
	v_mfma_f32_16x16x32_bf16 v[82:85], v[172:175], v[212:215], v[82:85]
	v_mfma_f32_16x16x32_bf16 v[70:73], v[164:167], v[220:223], v[70:73]
	v_mfma_f32_16x16x32_bf16 v[66:69], v[172:175], v[220:223], v[66:69]
	s_setprio 0
	s_barrier
	s_add_i32 s18, s18, s46
	v_lshl_add_u64 v[152:153], s[22:23], 0, v[132:133]
	s_mov_b32 m0, s18
	ds_read_b128 v[176:179], v155 offset:16384
	ds_read_b128 v[180:183], v155 offset:17408
	ds_read_b128 v[184:187], v155 offset:18432
	ds_read_b128 v[188:191], v155 offset:19456
	ds_read_b128 v[208:211], v155 offset:20480
	ds_read_b128 v[212:215], v155 offset:21504
	ds_read_b128 v[216:219], v155 offset:22528
	ds_read_b128 v[220:223], v155 offset:23552
	global_load_lds_dwordx4 v[152:153], off
	s_add_i32 m0, s18, 0x2000
	s_add_u32 s18, s22, 0x40000
	v_lshl_add_u64 v[192:193], s[22:23], 0, v[130:131]
	s_addc_u32 s19, s23, 0
	s_add_i32 s54, s54, s46
	global_load_lds_dwordx4 v[192:193], off
	v_lshl_add_u64 v[204:205], s[18:19], 0, v[132:133]
	s_mov_b32 m0, s54
	v_lshl_add_u64 v[224:225], s[8:9], 0, v[130:131]
	global_load_lds_dwordx4 v[204:205], off
	v_lshl_add_u64 v[204:205], s[18:19], 0, v[130:131]
	s_add_i32 m0, s54, 0x2000
	s_nop 0
	global_load_lds_dwordx4 v[204:205], off
	v_lshl_add_u64 v[204:205], s[8:9], 0, v[132:133]
	s_mov_b32 m0, s63
	s_nop 0
	global_load_lds_dwordx4 v[204:205], off
	s_mov_b32 m0, s64
	s_nop 0
	global_load_lds_dwordx4 v[224:225], off
	s_waitcnt vmcnt(8)
	s_waitcnt lgkmcnt(0)
	s_barrier
; #define PG8_STAGE_A(bufoff, gbase, spf) do { _Pragma("unroll") for (int _i = 0; _i < 2; ++_i) \
;         __builtin_amdgcn_global_load_lds((const unsigned*)((const char*)(gbase) + (Epi::SPECIAL_ROWS && (spf) ? voffS[_i] : voffA[_i])), (LAS unsigned*)(lds + (bufoff) + ldsw + _i * 8192), 16, 0, 0); } while (0)
; #define PG8_LDA(dst, b, h) do { _Pragma("unroll") for (int m = 0; m < 4; ++m) _Pragma("unroll") for (int k = 0; k < 2; ++k) dst[m][k] = *(const LAS bf16x8*)(lds + PG8_SA(b, h) + aoff + m * 2048 + k * 1024); } while (0)
; #define PG8_LDB(dst, b, h) do { _Pragma("unroll") for (int n = 0; n < 2; ++n) _Pragma("unroll") for (int k = 0; k < 2; ++k) dst[n][k] = *(const LAS bf16x8*)(lds + PG8_SB(b, h) + boff + n * 2048 + k * 1024); } while (0)
; #define PG8_MMA(ai, bj, At, Bt) do { __builtin_amdgcn_s_setprio(1); _Pragma("unroll") for (int m = 0; m < 4; ++m) _Pragma("unroll") for (int n = 0; n < 2; ++n) _Pragma("unroll") for (int k = 0; k < 2; ++k) \
;         acc[ai][bj][m][n] = __builtin_amdgcn_mfma_f32_16x16x32_bf16(Bt[n][k], At[m][k], acc[ai][bj][m][n], 0, 0, 0); __builtin_amdgcn_s_setprio(0); } while (0)
; #define PG8_WAIT_V(n) asm volatile("s_waitcnt vmcnt(" #n ")" ::: "memory")
; #define PG8_WAIT_L(n) asm volatile("s_waitcnt lgkmcnt(" #n ")" ::: "memory")
; #define PG8_BAR __builtin_amdgcn_s_barrier()
; #define PG8_SCHED __builtin_amdgcn_sched_barrier(0)
; template <class Epi>
; __device__ __forceinline__ void gemm_phase(LAS unsigned char* lds, const Gemm g, const Sched& S, const Epi& E) {
;     ...
;             PG8_WAIT_V(8); PG8_WAIT_L(0); PG8_BAR; PG8_MMA(1, 0, At, B0); PG8_MMA(1, 1, At, B1); PG8_BAR; PG8_SCHED;
;             PG8_LDB(B0, 1, 0); PG8_LDB(B1, 1, 1); PG8_SCHED; PG8_LDA(At, 1, 0); PG8_STAGE_A(PG8_SA(0, 1), a2 + hA2, sp2);
;             PG8_WAIT_V(8); PG8_WAIT_L(0); PG8_BAR; PG8_MMA(0, 0, At, B0); PG8_MMA(0, 1, At, B1); PG8_BAR; PG8_SCHED;
	s_setprio 1
	s_waitcnt lgkmcnt(0)
	v_mfma_f32_16x16x32_bf16 v[62:65], v[140:143], v[176:179], v[62:65]
	v_mfma_f32_16x16x32_bf16 v[58:61], v[148:151], v[176:179], v[58:61]
	v_mfma_f32_16x16x32_bf16 v[46:49], v[140:143], v[184:187], v[46:49]
	v_mfma_f32_16x16x32_bf16 v[42:45], v[148:151], v[184:187], v[42:45]
	v_mfma_f32_16x16x32_bf16 v[30:33], v[140:143], v[208:211], v[30:33]
	v_mfma_f32_16x16x32_bf16 v[26:29], v[148:151], v[208:211], v[26:29]
	v_mfma_f32_16x16x32_bf16 v[14:17], v[140:143], v[216:219], v[14:17]
	v_mfma_f32_16x16x32_bf16 v[10:13], v[148:151], v[216:219], v[10:13]
	v_mfma_f32_16x16x32_bf16 v[62:65], v[144:147], v[180:183], v[62:65]
	v_mfma_f32_16x16x32_bf16 v[58:61], v[156:159], v[180:183], v[58:61]
	v_mfma_f32_16x16x32_bf16 v[46:49], v[144:147], v[188:191], v[46:49]
	v_mfma_f32_16x16x32_bf16 v[42:45], v[156:159], v[188:191], v[42:45]
	v_mfma_f32_16x16x32_bf16 v[30:33], v[144:147], v[212:215], v[30:33]
	v_mfma_f32_16x16x32_bf16 v[26:29], v[156:159], v[212:215], v[26:29]
	v_mfma_f32_16x16x32_bf16 v[14:17], v[144:147], v[220:223], v[14:17]
	v_mfma_f32_16x16x32_bf16 v[10:13], v[156:159], v[220:223], v[10:13]
	s_setprio 0
	s_setprio 1
	v_mfma_f32_16x16x32_bf16 v[54:57], v[160:163], v[176:179], v[54:57]
	v_mfma_f32_16x16x32_bf16 v[50:53], v[168:171], v[176:179], v[50:53]
	v_mfma_f32_16x16x32_bf16 v[38:41], v[160:163], v[184:187], v[38:41]
	v_mfma_f32_16x16x32_bf16 v[34:37], v[168:171], v[184:187], v[34:37]
	v_mfma_f32_16x16x32_bf16 v[22:25], v[160:163], v[208:211], v[22:25]
	v_mfma_f32_16x16x32_bf16 v[18:21], v[168:171], v[208:211], v[18:21]
	v_mfma_f32_16x16x32_bf16 v[6:9], v[160:163], v[216:219], v[6:9]
	v_mfma_f32_16x16x32_bf16 v[2:5], v[168:171], v[216:219], v[2:5]
	v_mfma_f32_16x16x32_bf16 v[54:57], v[164:167], v[180:183], v[54:57]
	v_mfma_f32_16x16x32_bf16 v[50:53], v[172:175], v[180:183], v[50:53]
	v_mfma_f32_16x16x32_bf16 v[38:41], v[164:167], v[188:191], v[38:41]
	v_mfma_f32_16x16x32_bf16 v[34:37], v[172:175], v[188:191], v[34:37]
	v_mfma_f32_16x16x32_bf16 v[22:25], v[164:167], v[212:215], v[22:25]
	v_mfma_f32_16x16x32_bf16 v[18:21], v[172:175], v[212:215], v[18:21]
	v_mfma_f32_16x16x32_bf16 v[6:9], v[164:167], v[220:223], v[6:9]
	v_mfma_f32_16x16x32_bf16 v[2:5], v[172:175], v[220:223], v[2:5]
	s_setprio 0
	s_barrier
	s_add_i32 s18, 0, 0x18000
	s_add_i32 s19, 0, 0x1c000
	v_add_u32_e32 v156, s18, v154
	v_add_u32_e32 v172, s19, v154
	ds_read_b128 v[140:143], v156
	ds_read_b128 v[144:147], v156 offset:1024
	ds_read_b128 v[148:151], v156 offset:2048
	ds_read_b128 v[156:159], v156 offset:3072
	ds_read_b128 v[160:163], v172
	ds_read_b128 v[164:167], v172 offset:1024
	ds_read_b128 v[168:171], v172 offset:2048
	ds_read_b128 v[172:175], v172 offset:3072
	s_add_u32 s8, s8, 0x40000
	s_addc_u32 s9, s9, 0
	s_mov_b32 m0, s65
	v_lshl_add_u64 v[226:227], s[8:9], 0, v[132:133]
	ds_read_b128 v[176:179], v155 offset:32768
	ds_read_b128 v[180:183], v155 offset:33792
	ds_read_b128 v[184:187], v155 offset:34816
	ds_read_b128 v[188:191], v155 offset:35840
	ds_read_b128 v[208:211], v155 offset:36864
	ds_read_b128 v[212:215], v155 offset:37888
	ds_read_b128 v[216:219], v155 offset:38912
	ds_read_b128 v[220:223], v155 offset:39936
	global_load_lds_dwordx4 v[226:227], off
	v_lshl_add_u64 v[226:227], s[8:9], 0, v[130:131]
	s_mov_b32 m0, s72
	s_nop 0
	global_load_lds_dwordx4 v[226:227], off
	s_waitcnt vmcnt(8)
	s_waitcnt lgkmcnt(0)
	s_barrier
	s_setprio 1
	s_waitcnt lgkmcnt(0)
	v_mfma_f32_16x16x32_bf16 v[126:129], v[140:143], v[176:179], v[126:129]
	v_mfma_f32_16x16x32_bf16 v[122:125], v[148:151], v[176:179], v[122:125]
	v_mfma_f32_16x16x32_bf16 v[110:113], v[140:143], v[184:187], v[110:113]
	v_mfma_f32_16x16x32_bf16 v[106:109], v[148:151], v[184:187], v[106:109]
	v_mfma_f32_16x16x32_bf16 v[94:97], v[140:143], v[208:211], v[94:97]
	v_mfma_f32_16x16x32_bf16 v[90:93], v[148:151], v[208:211], v[90:93]
	v_mfma_f32_16x16x32_bf16 v[78:81], v[140:143], v[216:219], v[78:81]
	v_mfma_f32_16x16x32_bf16 v[74:77], v[148:151], v[216:219], v[74:77]
	v_mfma_f32_16x16x32_bf16 v[126:129], v[144:147], v[180:183], v[126:129]
	v_mfma_f32_16x16x32_bf16 v[122:125], v[156:159], v[180:183], v[122:125]
	v_mfma_f32_16x16x32_bf16 v[110:113], v[144:147], v[188:191], v[110:113]
	v_mfma_f32_16x16x32_bf16 v[106:109], v[156:159], v[188:191], v[106:109]
	v_mfma_f32_16x16x32_bf16 v[94:97], v[144:147], v[212:215], v[94:97]
	v_mfma_f32_16x16x32_bf16 v[90:93], v[156:159], v[212:215], v[90:93]
	v_mfma_f32_16x16x32_bf16 v[78:81], v[144:147], v[220:223], v[78:81]
	v_mfma_f32_16x16x32_bf16 v[74:77], v[156:159], v[220:223], v[74:77]
	s_setprio 0
	s_setprio 1
	v_mfma_f32_16x16x32_bf16 v[118:121], v[160:163], v[176:179], v[118:121]
	v_mfma_f32_16x16x32_bf16 v[114:117], v[168:171], v[176:179], v[114:117]
	v_mfma_f32_16x16x32_bf16 v[102:105], v[160:163], v[184:187], v[102:105]
	v_mfma_f32_16x16x32_bf16 v[98:101], v[168:171], v[184:187], v[98:101]
	v_mfma_f32_16x16x32_bf16 v[86:89], v[160:163], v[208:211], v[86:89]
	v_mfma_f32_16x16x32_bf16 v[82:85], v[168:171], v[208:211], v[82:85]
	v_mfma_f32_16x16x32_bf16 v[70:73], v[160:163], v[216:219], v[70:73]
	v_mfma_f32_16x16x32_bf16 v[66:69], v[168:171], v[216:219], v[66:69]
	v_mfma_f32_16x16x32_bf16 v[118:121], v[164:167], v[180:183], v[118:121]
	v_mfma_f32_16x16x32_bf16 v[114:117], v[172:175], v[180:183], v[114:117]
	v_mfma_f32_16x16x32_bf16 v[102:105], v[164:167], v[188:191], v[102:105]
	v_mfma_f32_16x16x32_bf16 v[98:101], v[172:175], v[188:191], v[98:101]
	v_mfma_f32_16x16x32_bf16 v[86:89], v[164:167], v[212:215], v[86:89]
	v_mfma_f32_16x16x32_bf16 v[82:85], v[172:175], v[212:215], v[82:85]
	v_mfma_f32_16x16x32_bf16 v[70:73], v[164:167], v[220:223], v[70:73]
	v_mfma_f32_16x16x32_bf16 v[66:69], v[172:175], v[220:223], v[66:69]
	s_setprio 0
	s_barrier
; #define PG8_STAGE(bufoff, gbase, voff) do { _Pragma("unroll") for (int _i = 0; _i < 2; ++_i) \
;         __builtin_amdgcn_global_load_lds((const unsigned*)((const char*)(gbase) + (voff)[_i]), (LAS unsigned*)(lds + (bufoff) + ldsw + _i * 8192), 16, 0, 0); } while (0)
; #define PG8_STAGE_A(bufoff, gbase, spf) do { _Pragma("unroll") for (int _i = 0; _i < 2; ++_i) \
;         __builtin_amdgcn_global_load_lds((const unsigned*)((const char*)(gbase) + (Epi::SPECIAL_ROWS && (spf) ? voffS[_i] : voffA[_i])), (LAS unsigned*)(lds + (bufoff) + ldsw + _i * 8192), 16, 0, 0); } while (0)
; #define PG8_LDA(dst, b, h) do { _Pragma("unroll") for (int m = 0; m < 4; ++m) _Pragma("unroll") for (int k = 0; k < 2; ++k) dst[m][k] = *(const LAS bf16x8*)(lds + PG8_SA(b, h) + aoff + m * 2048 + k * 1024); } while (0)
; #define PG8_MMA(ai, bj, At, Bt) do { __builtin_amdgcn_s_setprio(1); _Pragma("unroll") for (int m = 0; m < 4; ++m) _Pragma("unroll") for (int n = 0; n < 2; ++n) _Pragma("unroll") for (int k = 0; k < 2; ++k) \
;         acc[ai][bj][m][n] = __builtin_amdgcn_mfma_f32_16x16x32_bf16(Bt[n][k], At[m][k], acc[ai][bj][m][n], 0, 0, 0); __builtin_amdgcn_s_setprio(0); } while (0)
; #define PG8_WAIT_V(n) asm volatile("s_waitcnt vmcnt(" #n ")" ::: "memory")
; #define PG8_WAIT_L(n) asm volatile("s_waitcnt lgkmcnt(" #n ")" ::: "memory")
; #define PG8_BAR __builtin_amdgcn_s_barrier()
; #define PG8_SCHED __builtin_amdgcn_sched_barrier(0)
; template <class Epi>
; __device__ __forceinline__ void gemm_phase(LAS unsigned char* lds, const Gemm g, const Sched& S, const Epi& E) {
;     ...
;             PG8_LDA(At, 1, 1); PG8_STAGE(PG8_SB(1, 0), b3, voffB); PG8_STAGE(PG8_SB(1, 1), b3 + hstepB, voffB); PG8_STAGE_A(PG8_SA(1, 0), a3, sp2);
;             PG8_WAIT_V(8); PG8_WAIT_L(0); PG8_BAR; PG8_MMA(1, 0, At, B0); PG8_MMA(1, 1, At, B1); PG8_BAR; PG8_SCHED;
;         }
;         if (wr == 0) PG8_BAR;
	s_add_i32 s8, s18, s46
	v_lshl_add_u64 v[152:153], v[152:153], 0, s[20:21]
	s_mov_b32 m0, s8
	ds_read_b128 v[176:179], v155 offset:49152
	ds_read_b128 v[180:183], v155 offset:50176
	ds_read_b128 v[184:187], v155 offset:51200
	ds_read_b128 v[188:191], v155 offset:52224
	ds_read_b128 v[208:211], v155 offset:53248
	ds_read_b128 v[212:215], v155 offset:54272
	ds_read_b128 v[216:219], v155 offset:55296
	ds_read_b128 v[220:223], v155 offset:56320
	global_load_lds_dwordx4 v[152:153], off
	s_add_i32 m0, s8, 0x2000
	s_add_u32 s8, s22, 0x40080
	v_lshl_add_u64 v[152:153], v[192:193], 0, s[20:21]
	s_addc_u32 s9, s23, 0
	s_add_i32 s18, s19, s46
	global_load_lds_dwordx4 v[152:153], off
	v_lshl_add_u64 v[152:153], s[8:9], 0, v[132:133]
	s_mov_b32 m0, s18
	s_nop 0
	global_load_lds_dwordx4 v[152:153], off
	v_lshl_add_u64 v[152:153], s[8:9], 0, v[130:131]
	s_add_i32 m0, s18, 0x2000
	s_nop 0
	global_load_lds_dwordx4 v[152:153], off
	v_lshl_add_u64 v[152:153], v[204:205], 0, s[20:21]
	s_mov_b32 m0, s73
	s_nop 0
	global_load_lds_dwordx4 v[152:153], off
	v_lshl_add_u64 v[152:153], v[224:225], 0, s[20:21]
	s_mov_b32 m0, s74
	s_nop 0
	global_load_lds_dwordx4 v[152:153], off
	s_waitcnt vmcnt(8)
	s_waitcnt lgkmcnt(0)
	s_barrier
	s_setprio 1
	s_waitcnt lgkmcnt(0)
	v_mfma_f32_16x16x32_bf16 v[62:65], v[140:143], v[176:179], v[62:65]
	v_mfma_f32_16x16x32_bf16 v[58:61], v[148:151], v[176:179], v[58:61]
	v_mfma_f32_16x16x32_bf16 v[46:49], v[140:143], v[184:187], v[46:49]
	v_mfma_f32_16x16x32_bf16 v[42:45], v[148:151], v[184:187], v[42:45]
	v_mfma_f32_16x16x32_bf16 v[30:33], v[140:143], v[208:211], v[30:33]
	v_mfma_f32_16x16x32_bf16 v[26:29], v[148:151], v[208:211], v[26:29]
	v_mfma_f32_16x16x32_bf16 v[14:17], v[140:143], v[216:219], v[14:17]
	v_mfma_f32_16x16x32_bf16 v[10:13], v[148:151], v[216:219], v[10:13]
	v_mfma_f32_16x16x32_bf16 v[62:65], v[144:147], v[180:183], v[62:65]
	v_mfma_f32_16x16x32_bf16 v[58:61], v[156:159], v[180:183], v[58:61]
	v_mfma_f32_16x16x32_bf16 v[46:49], v[144:147], v[188:191], v[46:49]
	v_mfma_f32_16x16x32_bf16 v[42:45], v[156:159], v[188:191], v[42:45]
	v_mfma_f32_16x16x32_bf16 v[30:33], v[144:147], v[212:215], v[30:33]
	v_mfma_f32_16x16x32_bf16 v[26:29], v[156:159], v[212:215], v[26:29]
	v_mfma_f32_16x16x32_bf16 v[14:17], v[144:147], v[220:223], v[14:17]
	v_mfma_f32_16x16x32_bf16 v[10:13], v[156:159], v[220:223], v[10:13]
	s_setprio 0
	s_setprio 1
	v_mfma_f32_16x16x32_bf16 v[54:57], v[160:163], v[176:179], v[54:57]
	v_mfma_f32_16x16x32_bf16 v[50:53], v[168:171], v[176:179], v[50:53]
	v_mfma_f32_16x16x32_bf16 v[38:41], v[160:163], v[184:187], v[38:41]
	v_mfma_f32_16x16x32_bf16 v[34:37], v[168:171], v[184:187], v[34:37]
	v_mfma_f32_16x16x32_bf16 v[22:25], v[160:163], v[208:211], v[22:25]
	v_mfma_f32_16x16x32_bf16 v[18:21], v[168:171], v[208:211], v[18:21]
	v_mfma_f32_16x16x32_bf16 v[6:9], v[160:163], v[216:219], v[6:9]
	v_mfma_f32_16x16x32_bf16 v[2:5], v[168:171], v[216:219], v[2:5]
	v_mfma_f32_16x16x32_bf16 v[54:57], v[164:167], v[180:183], v[54:57]
	v_mfma_f32_16x16x32_bf16 v[50:53], v[172:175], v[180:183], v[50:53]
	v_mfma_f32_16x16x32_bf16 v[38:41], v[164:167], v[188:191], v[38:41]
	v_mfma_f32_16x16x32_bf16 v[34:37], v[172:175], v[188:191], v[34:37]
	v_mfma_f32_16x16x32_bf16 v[22:25], v[164:167], v[212:215], v[22:25]
	v_mfma_f32_16x16x32_bf16 v[18:21], v[172:175], v[212:215], v[18:21]
	v_mfma_f32_16x16x32_bf16 v[6:9], v[164:167], v[220:223], v[6:9]
	v_mfma_f32_16x16x32_bf16 v[2:5], v[172:175], v[220:223], v[2:5]
	s_setprio 0
	s_add_i32 s81, s81, 2
	s_add_u32 s12, s12, 0x100
	s_addc_u32 s13, s13, 0
	s_add_u32 s30, s30, 0x100
	s_addc_u32 s31, s31, 0
	s_barrier
	s_cmp_gt_u32 s81, 13
	s_cbranch_scc0 .LBB0_332
	s_and_b64 vcc, exec, s[14:15]
	s_cbranch_vccz .LBB0_335
	s_barrier

; #define PG8_STAGE(bufoff, gbase, voff) do { _Pragma("unroll") for (int _i = 0; _i < 2; ++_i) \
;         __builtin_amdgcn_global_load_lds((const unsigned*)((const char*)(gbase) + (voff)[_i]), (LAS unsigned*)(lds + (bufoff) + ldsw + _i * 8192), 16, 0, 0); } while (0)
; #define PG8_STAGE_A(bufoff, gbase, spf) do { _Pragma("unroll") for (int _i = 0; _i < 2; ++_i) \
;         __builtin_amdgcn_global_load_lds((const unsigned*)((const char*)(gbase) + (Epi::SPECIAL_ROWS && (spf) ? voffS[_i] : voffA[_i])), (LAS unsigned*)(lds + (bufoff) + ldsw + _i * 8192), 16, 0, 0); } while (0)
; #define PG8_LDA(dst, b, h) do { _Pragma("unroll") for (int m = 0; m < 4; ++m) _Pragma("unroll") for (int k = 0; k < 2; ++k) dst[m][k] = *(const LAS bf16x8*)(lds + PG8_SA(b, h) + aoff + m * 2048 + k * 1024); } while (0)
; #define PG8_LDB(dst, b, h) do { _Pragma("unroll") for (int n = 0; n < 2; ++n) _Pragma("unroll") for (int k = 0; k < 2; ++k) dst[n][k] = *(const LAS bf16x8*)(lds + PG8_SB(b, h) + boff + n * 2048 + k * 1024); } while (0)
; #define PG8_WAIT_V(n) asm volatile("s_waitcnt vmcnt(" #n ")" ::: "memory")
; #define PG8_WAIT_L(n) asm volatile("s_waitcnt lgkmcnt(" #n ")" ::: "memory")
; #define PG8_BAR __builtin_amdgcn_s_barrier()
; #define PG8_SCHED __builtin_amdgcn_sched_barrier(0)
; template <class Epi>
; __device__ __forceinline__ void gemm_phase(LAS unsigned char* lds, const Gemm g, const Sched& S, const Epi& E) {
;     ...
;             const char* a1 = cA + (size_t)((t + 1) & kmask) * kstep;
;             const char* a2 = last ? nA : cA + (size_t)((t + 2) & kmask) * kstep; const char* b2 = last ? nB : cB + (size_t)((t + 2) & kmask) * kstep;
;             const char* a3 = a2 + kstep; const char* b3 = b2 + kstep;
;             const bool sp2 = last ? nsp : csp; const size_t hA2 = last ? nhA : chA;
;             PG8_LDB(B0, 0, 0); PG8_LDB(B1, 0, 1); PG8_SCHED; PG8_LDA(At, 0, 0); PG8_STAGE_A(PG8_SA(1, 1), a1 + chA, csp);
;             PG8_WAIT_V(8); PG8_WAIT_L(0); PG8_BAR; PG8_MMA(0, 0, At, B0); PG8_MMA(0, 1, At, B1); PG8_BAR; PG8_SCHED;
;             PG8_LDA(At, 0, 1); PG8_STAGE(PG8_SB(0, 0), b2, voffB); PG8_STAGE(PG8_SB(0, 1), b2 + hstepB, voffB); PG8_STAGE_A(PG8_SA(0, 0), a2, sp2);
;             PG8_WAIT_V(8); PG8_WAIT_L(0); PG8_BAR; PG8_MMA(1, 0, At, B0); PG8_MMA(1, 1, At, B1); PG8_BAR; PG8_SCHED;
.LBB0_459:
	s_add_u32 s0, s74, 0x100
	s_addc_u32 s1, s75, 0
	s_add_i32 s18, 0, 0x10000
	s_cmp_eq_u32 s31, 2
	s_cselect_b32 s9, s79, s1
	s_cselect_b32 s8, s78, s0
	v_add_u32_e32 v0, s18, v179
	s_cselect_b32 s23, s77, s30
	s_cselect_b32 s22, s76, s13
	s_add_i32 s34, 0, 0x14000
	ds_read_b128 v[130:133], v0
	ds_read_b128 v[134:137], v0 offset:1024
	ds_read_b128 v[138:141], v0 offset:2048
	ds_read_b128 v[142:145], v0 offset:3072
	v_add_u32_e32 v0, s34, v179
	ds_read_b128 v[146:149], v0
	ds_read_b128 v[150:153], v0 offset:1024
	ds_read_b128 v[154:157], v0 offset:2048
	ds_read_b128 v[158:161], v0 offset:3072
	v_lshl_add_u64 v[204:205], s[74:75], 0, v[190:191]
	s_add_i32 m0, s46, 0xc000
	ds_read_b128 v[162:165], v175
	ds_read_b128 v[166:169], v175 offset:1024
	ds_read_b128 v[208:211], v175 offset:2048
	ds_read_b128 v[212:215], v175 offset:3072
	ds_read_b128 v[216:219], v175 offset:4096
	ds_read_b128 v[220:223], v175 offset:5120
	ds_read_b128 v[224:227], v175 offset:6144
	ds_read_b128 v[228:231], v175 offset:7168
	global_load_lds_dwordx4 v[204:205], off
	v_lshl_add_u64 v[204:205], s[74:75], 0, v[192:193]
	s_add_i32 m0, s46, 0xe000
	s_nop 0
	global_load_lds_dwordx4 v[204:205], off
	s_waitcnt vmcnt(8)
	s_waitcnt lgkmcnt(0)
	s_barrier
	s_setprio 1
	s_waitcnt lgkmcnt(0)
	v_mfma_f32_16x16x32_bf16 v[126:129], v[130:133], v[162:165], v[126:129]
	v_mfma_f32_16x16x32_bf16 v[122:125], v[138:141], v[162:165], v[122:125]
	v_mfma_f32_16x16x32_bf16 v[110:113], v[130:133], v[208:211], v[110:113]
	v_mfma_f32_16x16x32_bf16 v[106:109], v[138:141], v[208:211], v[106:109]
	v_mfma_f32_16x16x32_bf16 v[94:97], v[130:133], v[216:219], v[94:97]
	v_mfma_f32_16x16x32_bf16 v[90:93], v[138:141], v[216:219], v[90:93]
	v_mfma_f32_16x16x32_bf16 v[78:81], v[130:133], v[224:227], v[78:81]
	v_mfma_f32_16x16x32_bf16 v[74:77], v[138:141], v[224:227], v[74:77]
	v_mfma_f32_16x16x32_bf16 v[126:129], v[134:137], v[166:169], v[126:129]
	v_mfma_f32_16x16x32_bf16 v[122:125], v[142:145], v[166:169], v[122:125]
	v_mfma_f32_16x16x32_bf16 v[110:113], v[134:137], v[212:215], v[110:113]
	v_mfma_f32_16x16x32_bf16 v[106:109], v[142:145], v[212:215], v[106:109]
	v_mfma_f32_16x16x32_bf16 v[94:97], v[134:137], v[220:223], v[94:97]
	v_mfma_f32_16x16x32_bf16 v[90:93], v[142:145], v[220:223], v[90:93]
	v_mfma_f32_16x16x32_bf16 v[78:81], v[134:137], v[228:231], v[78:81]
	v_mfma_f32_16x16x32_bf16 v[74:77], v[142:145], v[228:231], v[74:77]
	s_setprio 0
	s_setprio 1
	v_mfma_f32_16x16x32_bf16 v[118:121], v[146:149], v[162:165], v[118:121]
	v_mfma_f32_16x16x32_bf16 v[114:117], v[154:157], v[162:165], v[114:117]
	v_mfma_f32_16x16x32_bf16 v[102:105], v[146:149], v[208:211], v[102:105]
	v_mfma_f32_16x16x32_bf16 v[98:101], v[154:157], v[208:211], v[98:101]
	v_mfma_f32_16x16x32_bf16 v[86:89], v[146:149], v[216:219], v[86:89]
	v_mfma_f32_16x16x32_bf16 v[82:85], v[154:157], v[216:219], v[82:85]
	v_mfma_f32_16x16x32_bf16 v[70:73], v[146:149], v[224:227], v[70:73]
	v_mfma_f32_16x16x32_bf16 v[66:69], v[154:157], v[224:227], v[66:69]
	v_mfma_f32_16x16x32_bf16 v[118:121], v[150:153], v[166:169], v[118:121]
	v_mfma_f32_16x16x32_bf16 v[114:117], v[158:161], v[166:169], v[114:117]
	v_mfma_f32_16x16x32_bf16 v[102:105], v[150:153], v[212:215], v[102:105]
	v_mfma_f32_16x16x32_bf16 v[98:101], v[158:161], v[212:215], v[98:101]
	v_mfma_f32_16x16x32_bf16 v[86:89], v[150:153], v[220:223], v[86:89]
	v_mfma_f32_16x16x32_bf16 v[82:85], v[158:161], v[220:223], v[82:85]
	v_mfma_f32_16x16x32_bf16 v[70:73], v[150:153], v[228:231], v[70:73]
	v_mfma_f32_16x16x32_bf16 v[66:69], v[158:161], v[228:231], v[66:69]
	s_setprio 0
	s_barrier
	s_add_i32 s18, s18, s37
	v_lshl_add_u64 v[204:205], s[22:23], 0, v[170:171]
	s_mov_b32 m0, s18
	ds_read_b128 v[162:165], v175 offset:16384
	ds_read_b128 v[166:169], v175 offset:17408
	ds_read_b128 v[208:211], v175 offset:18432
	ds_read_b128 v[212:215], v175 offset:19456
	ds_read_b128 v[216:219], v175 offset:20480
	ds_read_b128 v[220:223], v175 offset:21504
	ds_read_b128 v[224:227], v175 offset:22528
	ds_read_b128 v[228:231], v175 offset:23552
	global_load_lds_dwordx4 v[204:205], off
	s_add_i32 m0, s18, 0x2000
	s_add_u32 s18, s22, 0x18000
	v_lshl_add_u64 v[232:233], s[22:23], 0, v[172:173]
	s_addc_u32 s19, s23, 0
	s_add_i32 s34, s34, s37
	global_load_lds_dwordx4 v[232:233], off
	v_lshl_add_u64 v[234:235], s[18:19], 0, v[170:171]
	s_mov_b32 m0, s34
	v_lshl_add_u64 v[236:237], s[8:9], 0, v[172:173]
	global_load_lds_dwordx4 v[234:235], off
	v_lshl_add_u64 v[234:235], s[18:19], 0, v[172:173]
	s_add_i32 m0, s34, 0x2000
	s_nop 0
	global_load_lds_dwordx4 v[234:235], off
	v_lshl_add_u64 v[234:235], s[8:9], 0, v[170:171]
	s_mov_b32 m0, s46
	s_nop 0
	global_load_lds_dwordx4 v[234:235], off
	s_mov_b32 m0, s47
	s_nop 0
	global_load_lds_dwordx4 v[236:237], off
	s_waitcnt vmcnt(8)
	s_waitcnt lgkmcnt(0)
	s_barrier
; #define PG8_STAGE_A(bufoff, gbase, spf) do { _Pragma("unroll") for (int _i = 0; _i < 2; ++_i) \
;         __builtin_amdgcn_global_load_lds((const unsigned*)((const char*)(gbase) + (Epi::SPECIAL_ROWS && (spf) ? voffS[_i] : voffA[_i])), (LAS unsigned*)(lds + (bufoff) + ldsw + _i * 8192), 16, 0, 0); } while (0)
; #define PG8_LDA(dst, b, h) do { _Pragma("unroll") for (int m = 0; m < 4; ++m) _Pragma("unroll") for (int k = 0; k < 2; ++k) dst[m][k] = *(const LAS bf16x8*)(lds + PG8_SA(b, h) + aoff + m * 2048 + k * 1024); } while (0)
; #define PG8_LDB(dst, b, h) do { _Pragma("unroll") for (int n = 0; n < 2; ++n) _Pragma("unroll") for (int k = 0; k < 2; ++k) dst[n][k] = *(const LAS bf16x8*)(lds + PG8_SB(b, h) + boff + n * 2048 + k * 1024); } while (0)
; #define PG8_MMA(ai, bj, At, Bt) do { __builtin_amdgcn_s_setprio(1); _Pragma("unroll") for (int m = 0; m < 4; ++m) _Pragma("unroll") for (int n = 0; n < 2; ++n) _Pragma("unroll") for (int k = 0; k < 2; ++k) \
;         acc[ai][bj][m][n] = __builtin_amdgcn_mfma_f32_16x16x32_bf16(Bt[n][k], At[m][k], acc[ai][bj][m][n], 0, 0, 0); __builtin_amdgcn_s_setprio(0); } while (0)
; #define PG8_WAIT_V(n) asm volatile("s_waitcnt vmcnt(" #n ")" ::: "memory")
; #define PG8_WAIT_L(n) asm volatile("s_waitcnt lgkmcnt(" #n ")" ::: "memory")
; #define PG8_BAR __builtin_amdgcn_s_barrier()
; #define PG8_SCHED __builtin_amdgcn_sched_barrier(0)
; template <class Epi>
; __device__ __forceinline__ void gemm_phase(LAS unsigned char* lds, const Gemm g, const Sched& S, const Epi& E) {
;     ...
;             PG8_WAIT_V(8); PG8_WAIT_L(0); PG8_BAR; PG8_MMA(1, 0, At, B0); PG8_MMA(1, 1, At, B1); PG8_BAR; PG8_SCHED;
;             PG8_LDB(B0, 1, 0); PG8_LDB(B1, 1, 1); PG8_SCHED; PG8_LDA(At, 1, 0); PG8_STAGE_A(PG8_SA(0, 1), a2 + hA2, sp2);
;             PG8_WAIT_V(8); PG8_WAIT_L(0); PG8_BAR; PG8_MMA(0, 0, At, B0); PG8_MMA(0, 1, At, B1); PG8_BAR; PG8_SCHED;
	s_setprio 1
	s_waitcnt lgkmcnt(0)
	v_mfma_f32_16x16x32_bf16 v[62:65], v[130:133], v[162:165], v[62:65]
	v_mfma_f32_16x16x32_bf16 v[58:61], v[138:141], v[162:165], v[58:61]
	v_mfma_f32_16x16x32_bf16 v[46:49], v[130:133], v[208:211], v[46:49]
	v_mfma_f32_16x16x32_bf16 v[42:45], v[138:141], v[208:211], v[42:45]
	v_mfma_f32_16x16x32_bf16 v[30:33], v[130:133], v[216:219], v[30:33]
	v_mfma_f32_16x16x32_bf16 v[26:29], v[138:141], v[216:219], v[26:29]
	v_mfma_f32_16x16x32_bf16 v[14:17], v[130:133], v[224:227], v[14:17]
	v_mfma_f32_16x16x32_bf16 v[10:13], v[138:141], v[224:227], v[10:13]
	v_mfma_f32_16x16x32_bf16 v[62:65], v[134:137], v[166:169], v[62:65]
	v_mfma_f32_16x16x32_bf16 v[58:61], v[142:145], v[166:169], v[58:61]
	v_mfma_f32_16x16x32_bf16 v[46:49], v[134:137], v[212:215], v[46:49]
	v_mfma_f32_16x16x32_bf16 v[42:45], v[142:145], v[212:215], v[42:45]
	v_mfma_f32_16x16x32_bf16 v[30:33], v[134:137], v[220:223], v[30:33]
	v_mfma_f32_16x16x32_bf16 v[26:29], v[142:145], v[220:223], v[26:29]
	v_mfma_f32_16x16x32_bf16 v[14:17], v[134:137], v[228:231], v[14:17]
	v_mfma_f32_16x16x32_bf16 v[10:13], v[142:145], v[228:231], v[10:13]
	s_setprio 0
	s_setprio 1
	v_mfma_f32_16x16x32_bf16 v[54:57], v[146:149], v[162:165], v[54:57]
	v_mfma_f32_16x16x32_bf16 v[50:53], v[154:157], v[162:165], v[50:53]
	v_mfma_f32_16x16x32_bf16 v[38:41], v[146:149], v[208:211], v[38:41]
	v_mfma_f32_16x16x32_bf16 v[34:37], v[154:157], v[208:211], v[34:37]
	v_mfma_f32_16x16x32_bf16 v[22:25], v[146:149], v[216:219], v[22:25]
	v_mfma_f32_16x16x32_bf16 v[18:21], v[154:157], v[216:219], v[18:21]
	v_mfma_f32_16x16x32_bf16 v[6:9], v[146:149], v[224:227], v[6:9]
	v_mfma_f32_16x16x32_bf16 v[2:5], v[154:157], v[224:227], v[2:5]
	v_mfma_f32_16x16x32_bf16 v[54:57], v[150:153], v[166:169], v[54:57]
	v_mfma_f32_16x16x32_bf16 v[50:53], v[158:161], v[166:169], v[50:53]
	v_mfma_f32_16x16x32_bf16 v[38:41], v[150:153], v[212:215], v[38:41]
	v_mfma_f32_16x16x32_bf16 v[34:37], v[158:161], v[212:215], v[34:37]
	v_mfma_f32_16x16x32_bf16 v[22:25], v[150:153], v[220:223], v[22:25]
	v_mfma_f32_16x16x32_bf16 v[18:21], v[158:161], v[220:223], v[18:21]
	v_mfma_f32_16x16x32_bf16 v[6:9], v[150:153], v[228:231], v[6:9]
	v_mfma_f32_16x16x32_bf16 v[2:5], v[158:161], v[228:231], v[2:5]
	s_setprio 0
	s_barrier
	s_add_i32 s18, 0, 0x18000
	v_add_u32_e32 v0, s18, v179
	s_add_i32 s19, 0, 0x1c000
	ds_read_b128 v[130:133], v0
	ds_read_b128 v[134:137], v0 offset:1024
	ds_read_b128 v[138:141], v0 offset:2048
	ds_read_b128 v[142:145], v0 offset:3072
	v_add_u32_e32 v0, s19, v179
	ds_read_b128 v[146:149], v0
	ds_read_b128 v[150:153], v0 offset:1024
	ds_read_b128 v[154:157], v0 offset:2048
	ds_read_b128 v[158:161], v0 offset:3072
	s_add_u32 s8, s8, 0x18000
	s_addc_u32 s9, s9, 0
	s_mov_b32 m0, s63
	v_lshl_add_u64 v[238:239], s[8:9], 0, v[170:171]
	ds_read_b128 v[162:165], v175 offset:32768
	ds_read_b128 v[166:169], v175 offset:33792
	ds_read_b128 v[208:211], v175 offset:34816
	ds_read_b128 v[212:215], v175 offset:35840
	ds_read_b128 v[216:219], v175 offset:36864
	ds_read_b128 v[220:223], v175 offset:37888
	ds_read_b128 v[224:227], v175 offset:38912
	ds_read_b128 v[228:231], v175 offset:39936
	global_load_lds_dwordx4 v[238:239], off
	v_lshl_add_u64 v[238:239], s[8:9], 0, v[172:173]
	s_mov_b32 m0, s80
	s_nop 0
	global_load_lds_dwordx4 v[238:239], off
	s_waitcnt vmcnt(8)
	s_waitcnt lgkmcnt(0)
	s_barrier
	s_setprio 1
	s_waitcnt lgkmcnt(0)
	v_mfma_f32_16x16x32_bf16 v[126:129], v[130:133], v[162:165], v[126:129]
	v_mfma_f32_16x16x32_bf16 v[122:125], v[138:141], v[162:165], v[122:125]
	v_mfma_f32_16x16x32_bf16 v[110:113], v[130:133], v[208:211], v[110:113]
	v_mfma_f32_16x16x32_bf16 v[106:109], v[138:141], v[208:211], v[106:109]
	v_mfma_f32_16x16x32_bf16 v[94:97], v[130:133], v[216:219], v[94:97]
	v_mfma_f32_16x16x32_bf16 v[90:93], v[138:141], v[216:219], v[90:93]
	v_mfma_f32_16x16x32_bf16 v[78:81], v[130:133], v[224:227], v[78:81]
	v_mfma_f32_16x16x32_bf16 v[74:77], v[138:141], v[224:227], v[74:77]
	v_mfma_f32_16x16x32_bf16 v[126:129], v[134:137], v[166:169], v[126:129]
	v_mfma_f32_16x16x32_bf16 v[122:125], v[142:145], v[166:169], v[122:125]
	v_mfma_f32_16x16x32_bf16 v[110:113], v[134:137], v[212:215], v[110:113]
	v_mfma_f32_16x16x32_bf16 v[106:109], v[142:145], v[212:215], v[106:109]
	v_mfma_f32_16x16x32_bf16 v[94:97], v[134:137], v[220:223], v[94:97]
	v_mfma_f32_16x16x32_bf16 v[90:93], v[142:145], v[220:223], v[90:93]
	v_mfma_f32_16x16x32_bf16 v[78:81], v[134:137], v[228:231], v[78:81]
	v_mfma_f32_16x16x32_bf16 v[74:77], v[142:145], v[228:231], v[74:77]
	s_setprio 0
	s_setprio 1
	v_mfma_f32_16x16x32_bf16 v[118:121], v[146:149], v[162:165], v[118:121]
	v_mfma_f32_16x16x32_bf16 v[114:117], v[154:157], v[162:165], v[114:117]
	v_mfma_f32_16x16x32_bf16 v[102:105], v[146:149], v[208:211], v[102:105]
	v_mfma_f32_16x16x32_bf16 v[98:101], v[154:157], v[208:211], v[98:101]
	v_mfma_f32_16x16x32_bf16 v[86:89], v[146:149], v[216:219], v[86:89]
	v_mfma_f32_16x16x32_bf16 v[82:85], v[154:157], v[216:219], v[82:85]
	v_mfma_f32_16x16x32_bf16 v[70:73], v[146:149], v[224:227], v[70:73]
	v_mfma_f32_16x16x32_bf16 v[66:69], v[154:157], v[224:227], v[66:69]
	v_mfma_f32_16x16x32_bf16 v[118:121], v[150:153], v[166:169], v[118:121]
	v_mfma_f32_16x16x32_bf16 v[114:117], v[158:161], v[166:169], v[114:117]
	v_mfma_f32_16x16x32_bf16 v[102:105], v[150:153], v[212:215], v[102:105]
	v_mfma_f32_16x16x32_bf16 v[98:101], v[158:161], v[212:215], v[98:101]
	v_mfma_f32_16x16x32_bf16 v[86:89], v[150:153], v[220:223], v[86:89]
	v_mfma_f32_16x16x32_bf16 v[82:85], v[158:161], v[220:223], v[82:85]
	v_mfma_f32_16x16x32_bf16 v[70:73], v[150:153], v[228:231], v[70:73]
	v_mfma_f32_16x16x32_bf16 v[66:69], v[158:161], v[228:231], v[66:69]
	s_setprio 0
	s_barrier
; #define PG8_STAGE(bufoff, gbase, voff) do { _Pragma("unroll") for (int _i = 0; _i < 2; ++_i) \
;         __builtin_amdgcn_global_load_lds((const unsigned*)((const char*)(gbase) + (voff)[_i]), (LAS unsigned*)(lds + (bufoff) + ldsw + _i * 8192), 16, 0, 0); } while (0)
; #define PG8_STAGE_A(bufoff, gbase, spf) do { _Pragma("unroll") for (int _i = 0; _i < 2; ++_i) \
;         __builtin_amdgcn_global_load_lds((const unsigned*)((const char*)(gbase) + (Epi::SPECIAL_ROWS && (spf) ? voffS[_i] : voffA[_i])), (LAS unsigned*)(lds + (bufoff) + ldsw + _i * 8192), 16, 0, 0); } while (0)
; #define PG8_LDA(dst, b, h) do { _Pragma("unroll") for (int m = 0; m < 4; ++m) _Pragma("unroll") for (int k = 0; k < 2; ++k) dst[m][k] = *(const LAS bf16x8*)(lds + PG8_SA(b, h) + aoff + m * 2048 + k * 1024); } while (0)
; #define PG8_MMA(ai, bj, At, Bt) do { __builtin_amdgcn_s_setprio(1); _Pragma("unroll") for (int m = 0; m < 4; ++m) _Pragma("unroll") for (int n = 0; n < 2; ++n) _Pragma("unroll") for (int k = 0; k < 2; ++k) \
;         acc[ai][bj][m][n] = __builtin_amdgcn_mfma_f32_16x16x32_bf16(Bt[n][k], At[m][k], acc[ai][bj][m][n], 0, 0, 0); __builtin_amdgcn_s_setprio(0); } while (0)
; #define PG8_WAIT_V(n) asm volatile("s_waitcnt vmcnt(" #n ")" ::: "memory")
; #define PG8_WAIT_L(n) asm volatile("s_waitcnt lgkmcnt(" #n ")" ::: "memory")
; #define PG8_BAR __builtin_amdgcn_s_barrier()
; #define PG8_SCHED __builtin_amdgcn_sched_barrier(0)
; template <class Epi>
; __device__ __forceinline__ void gemm_phase(LAS unsigned char* lds, const Gemm g, const Sched& S, const Epi& E) {
;     ...
;             PG8_LDA(At, 1, 1); PG8_STAGE(PG8_SB(1, 0), b3, voffB); PG8_STAGE(PG8_SB(1, 1), b3 + hstepB, voffB); PG8_STAGE_A(PG8_SA(1, 0), a3, sp2);
;             PG8_WAIT_V(8); PG8_WAIT_L(0); PG8_BAR; PG8_MMA(1, 0, At, B0); PG8_MMA(1, 1, At, B1); PG8_BAR; PG8_SCHED;
;         }
;         if (wr == 0) PG8_BAR;
	s_add_i32 s8, s18, s37
	v_lshl_add_u64 v[204:205], v[204:205], 0, s[20:21]
	s_mov_b32 m0, s8
	ds_read_b128 v[162:165], v175 offset:49152
	ds_read_b128 v[166:169], v175 offset:50176
	ds_read_b128 v[208:211], v175 offset:51200
	ds_read_b128 v[212:215], v175 offset:52224
	ds_read_b128 v[216:219], v175 offset:53248
	ds_read_b128 v[220:223], v175 offset:54272
	ds_read_b128 v[224:227], v175 offset:55296
	ds_read_b128 v[228:231], v175 offset:56320
	global_load_lds_dwordx4 v[204:205], off
	s_add_i32 m0, s8, 0x2000
	s_add_u32 s8, s22, 0x18080
	v_lshl_add_u64 v[204:205], v[232:233], 0, s[20:21]
	s_addc_u32 s9, s23, 0
	s_add_i32 s18, s19, s37
	global_load_lds_dwordx4 v[204:205], off
	v_lshl_add_u64 v[204:205], s[8:9], 0, v[170:171]
	s_mov_b32 m0, s18
	s_nop 0
	global_load_lds_dwordx4 v[204:205], off
	v_lshl_add_u64 v[204:205], s[8:9], 0, v[172:173]
	s_add_i32 m0, s18, 0x2000
	s_nop 0
	global_load_lds_dwordx4 v[204:205], off
	v_lshl_add_u64 v[204:205], v[234:235], 0, s[20:21]
	s_mov_b32 m0, s81
	s_nop 0
	global_load_lds_dwordx4 v[204:205], off
	v_lshl_add_u64 v[204:205], v[236:237], 0, s[20:21]
	s_mov_b32 m0, s82
	s_nop 0
	global_load_lds_dwordx4 v[204:205], off
	s_waitcnt vmcnt(8)
	s_waitcnt lgkmcnt(0)
	s_barrier
	s_setprio 1
	s_waitcnt lgkmcnt(0)
	v_mfma_f32_16x16x32_bf16 v[62:65], v[130:133], v[162:165], v[62:65]
	v_mfma_f32_16x16x32_bf16 v[58:61], v[138:141], v[162:165], v[58:61]
	v_mfma_f32_16x16x32_bf16 v[46:49], v[130:133], v[208:211], v[46:49]
	v_mfma_f32_16x16x32_bf16 v[42:45], v[138:141], v[208:211], v[42:45]
	v_mfma_f32_16x16x32_bf16 v[30:33], v[130:133], v[216:219], v[30:33]
	v_mfma_f32_16x16x32_bf16 v[26:29], v[138:141], v[216:219], v[26:29]
	v_mfma_f32_16x16x32_bf16 v[14:17], v[130:133], v[224:227], v[14:17]
	v_mfma_f32_16x16x32_bf16 v[10:13], v[138:141], v[224:227], v[10:13]
	v_mfma_f32_16x16x32_bf16 v[62:65], v[134:137], v[166:169], v[62:65]
	v_mfma_f32_16x16x32_bf16 v[58:61], v[142:145], v[166:169], v[58:61]
	v_mfma_f32_16x16x32_bf16 v[46:49], v[134:137], v[212:215], v[46:49]
	v_mfma_f32_16x16x32_bf16 v[42:45], v[142:145], v[212:215], v[42:45]
	v_mfma_f32_16x16x32_bf16 v[30:33], v[134:137], v[220:223], v[30:33]
	v_mfma_f32_16x16x32_bf16 v[26:29], v[142:145], v[220:223], v[26:29]
	v_mfma_f32_16x16x32_bf16 v[14:17], v[134:137], v[228:231], v[14:17]
	v_mfma_f32_16x16x32_bf16 v[10:13], v[142:145], v[228:231], v[10:13]
	s_setprio 0
	s_setprio 1
	v_mfma_f32_16x16x32_bf16 v[54:57], v[146:149], v[162:165], v[54:57]
	v_mfma_f32_16x16x32_bf16 v[50:53], v[154:157], v[162:165], v[50:53]
	v_mfma_f32_16x16x32_bf16 v[38:41], v[146:149], v[208:211], v[38:41]
	v_mfma_f32_16x16x32_bf16 v[34:37], v[154:157], v[208:211], v[34:37]
	v_mfma_f32_16x16x32_bf16 v[22:25], v[146:149], v[216:219], v[22:25]
	v_mfma_f32_16x16x32_bf16 v[18:21], v[154:157], v[216:219], v[18:21]
	v_mfma_f32_16x16x32_bf16 v[6:9], v[146:149], v[224:227], v[6:9]
	v_mfma_f32_16x16x32_bf16 v[2:5], v[154:157], v[224:227], v[2:5]
	v_mfma_f32_16x16x32_bf16 v[54:57], v[150:153], v[166:169], v[54:57]
	v_mfma_f32_16x16x32_bf16 v[50:53], v[158:161], v[166:169], v[50:53]
	v_mfma_f32_16x16x32_bf16 v[38:41], v[150:153], v[212:215], v[38:41]
	v_mfma_f32_16x16x32_bf16 v[34:37], v[158:161], v[212:215], v[34:37]
	v_mfma_f32_16x16x32_bf16 v[22:25], v[150:153], v[220:223], v[22:25]
	v_mfma_f32_16x16x32_bf16 v[18:21], v[158:161], v[220:223], v[18:21]
	v_mfma_f32_16x16x32_bf16 v[6:9], v[150:153], v[228:231], v[6:9]
	v_mfma_f32_16x16x32_bf16 v[2:5], v[158:161], v[228:231], v[2:5]
	s_setprio 0
	s_add_i32 s31, s31, 2
	s_add_u32 s13, s13, 0x100
	s_addc_u32 s30, s30, 0
	s_barrier
	s_cmp_gt_u32 s31, 3
	s_mov_b64 s[74:75], s[0:1]
	s_cbranch_scc0 .LBB0_459
	s_and_b64 vcc, exec, s[38:39]
	s_cbranch_vccz .LBB0_462
	s_barrier

; #define PG8_STAGE(bufoff, gbase, voff) do { _Pragma("unroll") for (int _i = 0; _i < 2; ++_i) \
;         __builtin_amdgcn_global_load_lds((const unsigned*)((const char*)(gbase) + (voff)[_i]), (LAS unsigned*)(lds + (bufoff) + ldsw + _i * 8192), 16, 0, 0); } while (0)
; #define PG8_STAGE_A(bufoff, gbase, spf) do { _Pragma("unroll") for (int _i = 0; _i < 2; ++_i) \
;         __builtin_amdgcn_global_load_lds((const unsigned*)((const char*)(gbase) + (Epi::SPECIAL_ROWS && (spf) ? voffS[_i] : voffA[_i])), (LAS unsigned*)(lds + (bufoff) + ldsw + _i * 8192), 16, 0, 0); } while (0)
; #define PG8_LDA(dst, b, h) do { _Pragma("unroll") for (int m = 0; m < 4; ++m) _Pragma("unroll") for (int k = 0; k < 2; ++k) dst[m][k] = *(const LAS bf16x8*)(lds + PG8_SA(b, h) + aoff + m * 2048 + k * 1024); } while (0)
; #define PG8_LDB(dst, b, h) do { _Pragma("unroll") for (int n = 0; n < 2; ++n) _Pragma("unroll") for (int k = 0; k < 2; ++k) dst[n][k] = *(const LAS bf16x8*)(lds + PG8_SB(b, h) + boff + n * 2048 + k * 1024); } while (0)
; #define PG8_WAIT_V(n) asm volatile("s_waitcnt vmcnt(" #n ")" ::: "memory")
; #define PG8_WAIT_L(n) asm volatile("s_waitcnt lgkmcnt(" #n ")" ::: "memory")
; #define PG8_BAR __builtin_amdgcn_s_barrier()
; #define PG8_SCHED __builtin_amdgcn_sched_barrier(0)
; template <class Epi>
; __device__ __forceinline__ void gemm_phase(LAS unsigned char* lds, const Gemm g, const Sched& S, const Epi& E) {
;     ...
;             const char* a1 = cA + (size_t)((t + 1) & kmask) * kstep;
;             const char* a2 = last ? nA : cA + (size_t)((t + 2) & kmask) * kstep; const char* b2 = last ? nB : cB + (size_t)((t + 2) & kmask) * kstep;
;             const char* a3 = a2 + kstep; const char* b3 = b2 + kstep;
;             const bool sp2 = last ? nsp : csp; const size_t hA2 = last ? nhA : chA;
;             PG8_LDB(B0, 0, 0); PG8_LDB(B1, 0, 1); PG8_SCHED; PG8_LDA(At, 0, 0); PG8_STAGE_A(PG8_SA(1, 1), a1 + chA, csp);
;             PG8_WAIT_V(8); PG8_WAIT_L(0); PG8_BAR; PG8_MMA(0, 0, At, B0); PG8_MMA(0, 1, At, B1); PG8_BAR; PG8_SCHED;
;             PG8_LDA(At, 0, 1); PG8_STAGE(PG8_SB(0, 0), b2, voffB); PG8_STAGE(PG8_SB(0, 1), b2 + hstepB, voffB); PG8_STAGE_A(PG8_SA(0, 0), a2, sp2);
;             PG8_WAIT_V(8); PG8_WAIT_L(0); PG8_BAR; PG8_MMA(1, 0, At, B0); PG8_MMA(1, 1, At, B1); PG8_BAR; PG8_SCHED;
.LBB0_637:
	s_add_u32 s8, s12, 0xfffc0080
	s_addc_u32 s9, s13, -1
	s_add_i32 s34, 0, 0x10000
	s_cmp_eq_u32 s44, 12
	s_cselect_b32 s9, s1, s9
	s_cselect_b32 s8, s2, s8
	v_add_u32_e32 v0, s34, v135
	s_cselect_b32 s17, s22, s43
	s_cselect_b32 s16, s23, s42
	s_add_i32 s45, 0, 0x14000
	ds_read_b128 v[156:159], v0
	ds_read_b128 v[160:163], v0 offset:1024
	ds_read_b128 v[164:167], v0 offset:2048
	ds_read_b128 v[168:171], v0 offset:3072
	v_add_u32_e32 v0, s45, v135
	ds_read_b128 v[172:175], v0
	ds_read_b128 v[176:179], v0 offset:1024
	ds_read_b128 v[180:183], v0 offset:2048
	ds_read_b128 v[184:187], v0 offset:3072
	v_lshl_add_u64 v[192:193], s[12:13], 0, v[152:153]
	s_add_i32 m0, s19, 0xc000
	ds_read_b128 v[188:191], v139
	ds_read_b128 v[208:211], v139 offset:1024
	ds_read_b128 v[212:215], v139 offset:2048
	ds_read_b128 v[216:219], v139 offset:3072
	ds_read_b128 v[220:223], v139 offset:4096
	ds_read_b128 v[224:227], v139 offset:5120
	ds_read_b128 v[228:231], v139 offset:6144
	ds_read_b128 v[232:235], v139 offset:7168
	global_load_lds_dwordx4 v[192:193], off
	v_lshl_add_u64 v[192:193], s[12:13], 0, v[154:155]
	s_add_i32 m0, s19, 0xe000
	s_nop 0
	global_load_lds_dwordx4 v[192:193], off
	s_waitcnt vmcnt(8)
	s_waitcnt lgkmcnt(0)
	s_barrier
	s_setprio 1
	s_waitcnt lgkmcnt(0)
	v_mfma_f32_16x16x32_bf16 v[126:129], v[156:159], v[188:191], v[126:129]
	v_mfma_f32_16x16x32_bf16 v[122:125], v[164:167], v[188:191], v[122:125]
	v_mfma_f32_16x16x32_bf16 v[110:113], v[156:159], v[212:215], v[110:113]
	v_mfma_f32_16x16x32_bf16 v[106:109], v[164:167], v[212:215], v[106:109]
	v_mfma_f32_16x16x32_bf16 v[94:97], v[156:159], v[220:223], v[94:97]
	v_mfma_f32_16x16x32_bf16 v[90:93], v[164:167], v[220:223], v[90:93]
	v_mfma_f32_16x16x32_bf16 v[78:81], v[156:159], v[228:231], v[78:81]
	v_mfma_f32_16x16x32_bf16 v[74:77], v[164:167], v[228:231], v[74:77]
	v_mfma_f32_16x16x32_bf16 v[126:129], v[160:163], v[208:211], v[126:129]
	v_mfma_f32_16x16x32_bf16 v[122:125], v[168:171], v[208:211], v[122:125]
	v_mfma_f32_16x16x32_bf16 v[110:113], v[160:163], v[216:219], v[110:113]
	v_mfma_f32_16x16x32_bf16 v[106:109], v[168:171], v[216:219], v[106:109]
	v_mfma_f32_16x16x32_bf16 v[94:97], v[160:163], v[224:227], v[94:97]
	v_mfma_f32_16x16x32_bf16 v[90:93], v[168:171], v[224:227], v[90:93]
	v_mfma_f32_16x16x32_bf16 v[78:81], v[160:163], v[232:235], v[78:81]
	v_mfma_f32_16x16x32_bf16 v[74:77], v[168:171], v[232:235], v[74:77]
	s_setprio 0
	s_setprio 1
	v_mfma_f32_16x16x32_bf16 v[118:121], v[172:175], v[188:191], v[118:121]
	v_mfma_f32_16x16x32_bf16 v[114:117], v[180:183], v[188:191], v[114:117]
	v_mfma_f32_16x16x32_bf16 v[102:105], v[172:175], v[212:215], v[102:105]
	v_mfma_f32_16x16x32_bf16 v[98:101], v[180:183], v[212:215], v[98:101]
	v_mfma_f32_16x16x32_bf16 v[86:89], v[172:175], v[220:223], v[86:89]
	v_mfma_f32_16x16x32_bf16 v[82:85], v[180:183], v[220:223], v[82:85]
	v_mfma_f32_16x16x32_bf16 v[70:73], v[172:175], v[228:231], v[70:73]
	v_mfma_f32_16x16x32_bf16 v[66:69], v[180:183], v[228:231], v[66:69]
	v_mfma_f32_16x16x32_bf16 v[118:121], v[176:179], v[208:211], v[118:121]
	v_mfma_f32_16x16x32_bf16 v[114:117], v[184:187], v[208:211], v[114:117]
	v_mfma_f32_16x16x32_bf16 v[102:105], v[176:179], v[216:219], v[102:105]
	v_mfma_f32_16x16x32_bf16 v[98:101], v[184:187], v[216:219], v[98:101]
	v_mfma_f32_16x16x32_bf16 v[86:89], v[176:179], v[224:227], v[86:89]
	v_mfma_f32_16x16x32_bf16 v[82:85], v[184:187], v[224:227], v[82:85]
	v_mfma_f32_16x16x32_bf16 v[70:73], v[176:179], v[232:235], v[70:73]
	v_mfma_f32_16x16x32_bf16 v[66:69], v[184:187], v[232:235], v[66:69]
	s_setprio 0
	s_barrier
	s_add_i32 s34, s34, s46
	v_lshl_add_u64 v[192:193], s[16:17], 0, v[130:131]
	s_mov_b32 m0, s34
	ds_read_b128 v[188:191], v139 offset:16384
	ds_read_b128 v[208:211], v139 offset:17408
	ds_read_b128 v[212:215], v139 offset:18432
	ds_read_b128 v[216:219], v139 offset:19456
	ds_read_b128 v[220:223], v139 offset:20480
	ds_read_b128 v[224:227], v139 offset:21504
	ds_read_b128 v[228:231], v139 offset:22528
	ds_read_b128 v[232:235], v139 offset:23552
	global_load_lds_dwordx4 v[192:193], off
	s_add_i32 m0, s34, 0x2000
	s_add_u32 s34, s16, 0x40000
	v_lshl_add_u64 v[204:205], s[16:17], 0, v[132:133]
	s_addc_u32 s35, s17, 0
	s_add_i32 s45, s45, s46
	global_load_lds_dwordx4 v[204:205], off
	v_lshl_add_u64 v[236:237], s[34:35], 0, v[130:131]
	s_mov_b32 m0, s45
	v_lshl_add_u64 v[238:239], s[8:9], 0, v[132:133]
	global_load_lds_dwordx4 v[236:237], off
	v_lshl_add_u64 v[236:237], s[34:35], 0, v[132:133]
	s_add_i32 m0, s45, 0x2000
	s_nop 0
	global_load_lds_dwordx4 v[236:237], off
	v_lshl_add_u64 v[236:237], s[8:9], 0, v[130:131]
	s_mov_b32 m0, s19
	s_nop 0
	global_load_lds_dwordx4 v[236:237], off
	s_mov_b32 m0, s80
	s_nop 0
	global_load_lds_dwordx4 v[238:239], off
	s_waitcnt vmcnt(8)
	s_waitcnt lgkmcnt(0)
	s_barrier
; #define PG8_STAGE_A(bufoff, gbase, spf) do { _Pragma("unroll") for (int _i = 0; _i < 2; ++_i) \
;         __builtin_amdgcn_global_load_lds((const unsigned*)((const char*)(gbase) + (Epi::SPECIAL_ROWS && (spf) ? voffS[_i] : voffA[_i])), (LAS unsigned*)(lds + (bufoff) + ldsw + _i * 8192), 16, 0, 0); } while (0)
; #define PG8_LDA(dst, b, h) do { _Pragma("unroll") for (int m = 0; m < 4; ++m) _Pragma("unroll") for (int k = 0; k < 2; ++k) dst[m][k] = *(const LAS bf16x8*)(lds + PG8_SA(b, h) + aoff + m * 2048 + k * 1024); } while (0)
; #define PG8_LDB(dst, b, h) do { _Pragma("unroll") for (int n = 0; n < 2; ++n) _Pragma("unroll") for (int k = 0; k < 2; ++k) dst[n][k] = *(const LAS bf16x8*)(lds + PG8_SB(b, h) + boff + n * 2048 + k * 1024); } while (0)
; #define PG8_MMA(ai, bj, At, Bt) do { __builtin_amdgcn_s_setprio(1); _Pragma("unroll") for (int m = 0; m < 4; ++m) _Pragma("unroll") for (int n = 0; n < 2; ++n) _Pragma("unroll") for (int k = 0; k < 2; ++k) \
;         acc[ai][bj][m][n] = __builtin_amdgcn_mfma_f32_16x16x32_bf16(Bt[n][k], At[m][k], acc[ai][bj][m][n], 0, 0, 0); __builtin_amdgcn_s_setprio(0); } while (0)
; #define PG8_WAIT_V(n) asm volatile("s_waitcnt vmcnt(" #n ")" ::: "memory")
; #define PG8_WAIT_L(n) asm volatile("s_waitcnt lgkmcnt(" #n ")" ::: "memory")
; #define PG8_BAR __builtin_amdgcn_s_barrier()
; #define PG8_SCHED __builtin_amdgcn_sched_barrier(0)
; template <class Epi>
; __device__ __forceinline__ void gemm_phase(LAS unsigned char* lds, const Gemm g, const Sched& S, const Epi& E) {
;     ...
;             PG8_WAIT_V(8); PG8_WAIT_L(0); PG8_BAR; PG8_MMA(1, 0, At, B0); PG8_MMA(1, 1, At, B1); PG8_BAR; PG8_SCHED;
;             PG8_LDB(B0, 1, 0); PG8_LDB(B1, 1, 1); PG8_SCHED; PG8_LDA(At, 1, 0); PG8_STAGE_A(PG8_SA(0, 1), a2 + hA2, sp2);
;             PG8_WAIT_V(8); PG8_WAIT_L(0); PG8_BAR; PG8_MMA(0, 0, At, B0); PG8_MMA(0, 1, At, B1); PG8_BAR; PG8_SCHED;
	s_setprio 1
	s_waitcnt lgkmcnt(0)
	v_mfma_f32_16x16x32_bf16 v[62:65], v[156:159], v[188:191], v[62:65]
	v_mfma_f32_16x16x32_bf16 v[58:61], v[164:167], v[188:191], v[58:61]
	v_mfma_f32_16x16x32_bf16 v[46:49], v[156:159], v[212:215], v[46:49]
	v_mfma_f32_16x16x32_bf16 v[42:45], v[164:167], v[212:215], v[42:45]
	v_mfma_f32_16x16x32_bf16 v[30:33], v[156:159], v[220:223], v[30:33]
	v_mfma_f32_16x16x32_bf16 v[26:29], v[164:167], v[220:223], v[26:29]
	v_mfma_f32_16x16x32_bf16 v[14:17], v[156:159], v[228:231], v[14:17]
	v_mfma_f32_16x16x32_bf16 v[10:13], v[164:167], v[228:231], v[10:13]
	v_mfma_f32_16x16x32_bf16 v[62:65], v[160:163], v[208:211], v[62:65]
	v_mfma_f32_16x16x32_bf16 v[58:61], v[168:171], v[208:211], v[58:61]
	v_mfma_f32_16x16x32_bf16 v[46:49], v[160:163], v[216:219], v[46:49]
	v_mfma_f32_16x16x32_bf16 v[42:45], v[168:171], v[216:219], v[42:45]
	v_mfma_f32_16x16x32_bf16 v[30:33], v[160:163], v[224:227], v[30:33]
	v_mfma_f32_16x16x32_bf16 v[26:29], v[168:171], v[224:227], v[26:29]
	v_mfma_f32_16x16x32_bf16 v[14:17], v[160:163], v[232:235], v[14:17]
	v_mfma_f32_16x16x32_bf16 v[10:13], v[168:171], v[232:235], v[10:13]
	s_setprio 0
	s_setprio 1
	v_mfma_f32_16x16x32_bf16 v[54:57], v[172:175], v[188:191], v[54:57]
	v_mfma_f32_16x16x32_bf16 v[50:53], v[180:183], v[188:191], v[50:53]
	v_mfma_f32_16x16x32_bf16 v[38:41], v[172:175], v[212:215], v[38:41]
	v_mfma_f32_16x16x32_bf16 v[34:37], v[180:183], v[212:215], v[34:37]
	v_mfma_f32_16x16x32_bf16 v[22:25], v[172:175], v[220:223], v[22:25]
	v_mfma_f32_16x16x32_bf16 v[18:21], v[180:183], v[220:223], v[18:21]
	v_mfma_f32_16x16x32_bf16 v[6:9], v[172:175], v[228:231], v[6:9]
	v_mfma_f32_16x16x32_bf16 v[2:5], v[180:183], v[228:231], v[2:5]
	v_mfma_f32_16x16x32_bf16 v[54:57], v[176:179], v[208:211], v[54:57]
	v_mfma_f32_16x16x32_bf16 v[50:53], v[184:187], v[208:211], v[50:53]
	v_mfma_f32_16x16x32_bf16 v[38:41], v[176:179], v[216:219], v[38:41]
	v_mfma_f32_16x16x32_bf16 v[34:37], v[184:187], v[216:219], v[34:37]
	v_mfma_f32_16x16x32_bf16 v[22:25], v[176:179], v[224:227], v[22:25]
	v_mfma_f32_16x16x32_bf16 v[18:21], v[184:187], v[224:227], v[18:21]
	v_mfma_f32_16x16x32_bf16 v[6:9], v[176:179], v[232:235], v[6:9]
	v_mfma_f32_16x16x32_bf16 v[2:5], v[184:187], v[232:235], v[2:5]
	s_setprio 0
	s_barrier
	s_add_i32 s34, 0, 0x18000
	v_add_u32_e32 v0, s34, v135
	s_add_i32 s35, 0, 0x1c000
	ds_read_b128 v[156:159], v0
	ds_read_b128 v[160:163], v0 offset:1024
	ds_read_b128 v[164:167], v0 offset:2048
	ds_read_b128 v[168:171], v0 offset:3072
	v_add_u32_e32 v0, s35, v135
	ds_read_b128 v[172:175], v0
	ds_read_b128 v[176:179], v0 offset:1024
	ds_read_b128 v[180:183], v0 offset:2048
	ds_read_b128 v[184:187], v0 offset:3072
	s_add_u32 s8, s8, 0x40000
	s_addc_u32 s9, s9, 0
	s_mov_b32 m0, s81
	v_lshl_add_u64 v[240:241], s[8:9], 0, v[130:131]
	ds_read_b128 v[188:191], v139 offset:32768
	ds_read_b128 v[208:211], v139 offset:33792
	ds_read_b128 v[212:215], v139 offset:34816
	ds_read_b128 v[216:219], v139 offset:35840
	ds_read_b128 v[220:223], v139 offset:36864
	ds_read_b128 v[224:227], v139 offset:37888
	ds_read_b128 v[228:231], v139 offset:38912
	ds_read_b128 v[232:235], v139 offset:39936
	global_load_lds_dwordx4 v[240:241], off
	v_lshl_add_u64 v[240:241], s[8:9], 0, v[132:133]
	s_mov_b32 m0, s82
	s_nop 0
	global_load_lds_dwordx4 v[240:241], off
	s_waitcnt vmcnt(8)
	s_waitcnt lgkmcnt(0)
	s_barrier
	s_setprio 1
	s_waitcnt lgkmcnt(0)
	v_mfma_f32_16x16x32_bf16 v[126:129], v[156:159], v[188:191], v[126:129]
	v_mfma_f32_16x16x32_bf16 v[122:125], v[164:167], v[188:191], v[122:125]
	v_mfma_f32_16x16x32_bf16 v[110:113], v[156:159], v[212:215], v[110:113]
	v_mfma_f32_16x16x32_bf16 v[106:109], v[164:167], v[212:215], v[106:109]
	v_mfma_f32_16x16x32_bf16 v[94:97], v[156:159], v[220:223], v[94:97]
	v_mfma_f32_16x16x32_bf16 v[90:93], v[164:167], v[220:223], v[90:93]
	v_mfma_f32_16x16x32_bf16 v[78:81], v[156:159], v[228:231], v[78:81]
	v_mfma_f32_16x16x32_bf16 v[74:77], v[164:167], v[228:231], v[74:77]
	v_mfma_f32_16x16x32_bf16 v[126:129], v[160:163], v[208:211], v[126:129]
	v_mfma_f32_16x16x32_bf16 v[122:125], v[168:171], v[208:211], v[122:125]
	v_mfma_f32_16x16x32_bf16 v[110:113], v[160:163], v[216:219], v[110:113]
	v_mfma_f32_16x16x32_bf16 v[106:109], v[168:171], v[216:219], v[106:109]
	v_mfma_f32_16x16x32_bf16 v[94:97], v[160:163], v[224:227], v[94:97]
	v_mfma_f32_16x16x32_bf16 v[90:93], v[168:171], v[224:227], v[90:93]
	v_mfma_f32_16x16x32_bf16 v[78:81], v[160:163], v[232:235], v[78:81]
	v_mfma_f32_16x16x32_bf16 v[74:77], v[168:171], v[232:235], v[74:77]
	s_setprio 0
	s_setprio 1
	v_mfma_f32_16x16x32_bf16 v[118:121], v[172:175], v[188:191], v[118:121]
	v_mfma_f32_16x16x32_bf16 v[114:117], v[180:183], v[188:191], v[114:117]
	v_mfma_f32_16x16x32_bf16 v[102:105], v[172:175], v[212:215], v[102:105]
	v_mfma_f32_16x16x32_bf16 v[98:101], v[180:183], v[212:215], v[98:101]
	v_mfma_f32_16x16x32_bf16 v[86:89], v[172:175], v[220:223], v[86:89]
	v_mfma_f32_16x16x32_bf16 v[82:85], v[180:183], v[220:223], v[82:85]
	v_mfma_f32_16x16x32_bf16 v[70:73], v[172:175], v[228:231], v[70:73]
	v_mfma_f32_16x16x32_bf16 v[66:69], v[180:183], v[228:231], v[66:69]
	v_mfma_f32_16x16x32_bf16 v[118:121], v[176:179], v[208:211], v[118:121]
	v_mfma_f32_16x16x32_bf16 v[114:117], v[184:187], v[208:211], v[114:117]
	v_mfma_f32_16x16x32_bf16 v[102:105], v[176:179], v[216:219], v[102:105]
	v_mfma_f32_16x16x32_bf16 v[98:101], v[184:187], v[216:219], v[98:101]
	v_mfma_f32_16x16x32_bf16 v[86:89], v[176:179], v[224:227], v[86:89]
	v_mfma_f32_16x16x32_bf16 v[82:85], v[184:187], v[224:227], v[82:85]
	v_mfma_f32_16x16x32_bf16 v[70:73], v[176:179], v[232:235], v[70:73]
	v_mfma_f32_16x16x32_bf16 v[66:69], v[184:187], v[232:235], v[66:69]
	s_setprio 0
	s_barrier
; #define PG8_STAGE(bufoff, gbase, voff) do { _Pragma("unroll") for (int _i = 0; _i < 2; ++_i) \
;         __builtin_amdgcn_global_load_lds((const unsigned*)((const char*)(gbase) + (voff)[_i]), (LAS unsigned*)(lds + (bufoff) + ldsw + _i * 8192), 16, 0, 0); } while (0)
; #define PG8_STAGE_A(bufoff, gbase, spf) do { _Pragma("unroll") for (int _i = 0; _i < 2; ++_i) \
;         __builtin_amdgcn_global_load_lds((const unsigned*)((const char*)(gbase) + (Epi::SPECIAL_ROWS && (spf) ? voffS[_i] : voffA[_i])), (LAS unsigned*)(lds + (bufoff) + ldsw + _i * 8192), 16, 0, 0); } while (0)
; #define PG8_LDA(dst, b, h) do { _Pragma("unroll") for (int m = 0; m < 4; ++m) _Pragma("unroll") for (int k = 0; k < 2; ++k) dst[m][k] = *(const LAS bf16x8*)(lds + PG8_SA(b, h) + aoff + m * 2048 + k * 1024); } while (0)
; #define PG8_MMA(ai, bj, At, Bt) do { __builtin_amdgcn_s_setprio(1); _Pragma("unroll") for (int m = 0; m < 4; ++m) _Pragma("unroll") for (int n = 0; n < 2; ++n) _Pragma("unroll") for (int k = 0; k < 2; ++k) \
;         acc[ai][bj][m][n] = __builtin_amdgcn_mfma_f32_16x16x32_bf16(Bt[n][k], At[m][k], acc[ai][bj][m][n], 0, 0, 0); __builtin_amdgcn_s_setprio(0); } while (0)
; #define PG8_WAIT_V(n) asm volatile("s_waitcnt vmcnt(" #n ")" ::: "memory")
; #define PG8_WAIT_L(n) asm volatile("s_waitcnt lgkmcnt(" #n ")" ::: "memory")
; #define PG8_BAR __builtin_amdgcn_s_barrier()
; #define PG8_SCHED __builtin_amdgcn_sched_barrier(0)
; template <class Epi>
; __device__ __forceinline__ void gemm_phase(LAS unsigned char* lds, const Gemm g, const Sched& S, const Epi& E) {
;     ...
;             PG8_LDA(At, 1, 1); PG8_STAGE(PG8_SB(1, 0), b3, voffB); PG8_STAGE(PG8_SB(1, 1), b3 + hstepB, voffB); PG8_STAGE_A(PG8_SA(1, 0), a3, sp2);
;             PG8_WAIT_V(8); PG8_WAIT_L(0); PG8_BAR; PG8_MMA(1, 0, At, B0); PG8_MMA(1, 1, At, B1); PG8_BAR; PG8_SCHED;
;         }
;         if (wr == 0) PG8_BAR;
	s_add_i32 s8, s34, s46
	v_lshl_add_u64 v[192:193], v[192:193], 0, s[20:21]
	s_mov_b32 m0, s8
	ds_read_b128 v[188:191], v139 offset:49152
	ds_read_b128 v[208:211], v139 offset:50176
	ds_read_b128 v[212:215], v139 offset:51200
	ds_read_b128 v[216:219], v139 offset:52224
	ds_read_b128 v[220:223], v139 offset:53248
	ds_read_b128 v[224:227], v139 offset:54272
	ds_read_b128 v[228:231], v139 offset:55296
	ds_read_b128 v[232:235], v139 offset:56320
	global_load_lds_dwordx4 v[192:193], off
	s_add_i32 m0, s8, 0x2000
	s_add_u32 s8, s16, 0x40080
	v_lshl_add_u64 v[192:193], v[204:205], 0, s[20:21]
	s_addc_u32 s9, s17, 0
	s_add_i32 s16, s35, s46
	global_load_lds_dwordx4 v[192:193], off
	v_lshl_add_u64 v[192:193], s[8:9], 0, v[130:131]
	s_mov_b32 m0, s16
	s_nop 0
	global_load_lds_dwordx4 v[192:193], off
	v_lshl_add_u64 v[192:193], s[8:9], 0, v[132:133]
	s_add_i32 m0, s16, 0x2000
	s_nop 0
	global_load_lds_dwordx4 v[192:193], off
	v_lshl_add_u64 v[192:193], v[236:237], 0, s[20:21]
	s_mov_b32 m0, s83
	s_nop 0
	global_load_lds_dwordx4 v[192:193], off
	v_lshl_add_u64 v[192:193], v[238:239], 0, s[20:21]
	s_mov_b32 m0, s84
	s_nop 0
	global_load_lds_dwordx4 v[192:193], off
	s_waitcnt vmcnt(8)
	s_waitcnt lgkmcnt(0)
	s_barrier
	s_setprio 1
	s_waitcnt lgkmcnt(0)
	v_mfma_f32_16x16x32_bf16 v[62:65], v[156:159], v[188:191], v[62:65]
	v_mfma_f32_16x16x32_bf16 v[58:61], v[164:167], v[188:191], v[58:61]
	v_mfma_f32_16x16x32_bf16 v[46:49], v[156:159], v[212:215], v[46:49]
	v_mfma_f32_16x16x32_bf16 v[42:45], v[164:167], v[212:215], v[42:45]
	v_mfma_f32_16x16x32_bf16 v[30:33], v[156:159], v[220:223], v[30:33]
	v_mfma_f32_16x16x32_bf16 v[26:29], v[164:167], v[220:223], v[26:29]
	v_mfma_f32_16x16x32_bf16 v[14:17], v[156:159], v[228:231], v[14:17]
	v_mfma_f32_16x16x32_bf16 v[10:13], v[164:167], v[228:231], v[10:13]
	v_mfma_f32_16x16x32_bf16 v[62:65], v[160:163], v[208:211], v[62:65]
	v_mfma_f32_16x16x32_bf16 v[58:61], v[168:171], v[208:211], v[58:61]
	v_mfma_f32_16x16x32_bf16 v[46:49], v[160:163], v[216:219], v[46:49]
	v_mfma_f32_16x16x32_bf16 v[42:45], v[168:171], v[216:219], v[42:45]
	v_mfma_f32_16x16x32_bf16 v[30:33], v[160:163], v[224:227], v[30:33]
	v_mfma_f32_16x16x32_bf16 v[26:29], v[168:171], v[224:227], v[26:29]
	v_mfma_f32_16x16x32_bf16 v[14:17], v[160:163], v[232:235], v[14:17]
	v_mfma_f32_16x16x32_bf16 v[10:13], v[168:171], v[232:235], v[10:13]
	s_setprio 0
	s_setprio 1
	v_mfma_f32_16x16x32_bf16 v[54:57], v[172:175], v[188:191], v[54:57]
	v_mfma_f32_16x16x32_bf16 v[50:53], v[180:183], v[188:191], v[50:53]
	v_mfma_f32_16x16x32_bf16 v[38:41], v[172:175], v[212:215], v[38:41]
	v_mfma_f32_16x16x32_bf16 v[34:37], v[180:183], v[212:215], v[34:37]
	v_mfma_f32_16x16x32_bf16 v[22:25], v[172:175], v[220:223], v[22:25]
	v_mfma_f32_16x16x32_bf16 v[18:21], v[180:183], v[220:223], v[18:21]
	v_mfma_f32_16x16x32_bf16 v[6:9], v[172:175], v[228:231], v[6:9]
	v_mfma_f32_16x16x32_bf16 v[2:5], v[180:183], v[228:231], v[2:5]
	v_mfma_f32_16x16x32_bf16 v[54:57], v[176:179], v[208:211], v[54:57]
	v_mfma_f32_16x16x32_bf16 v[50:53], v[184:187], v[208:211], v[50:53]
	v_mfma_f32_16x16x32_bf16 v[38:41], v[176:179], v[216:219], v[38:41]
	v_mfma_f32_16x16x32_bf16 v[34:37], v[184:187], v[216:219], v[34:37]
	v_mfma_f32_16x16x32_bf16 v[22:25], v[176:179], v[224:227], v[22:25]
	v_mfma_f32_16x16x32_bf16 v[18:21], v[184:187], v[224:227], v[18:21]
	v_mfma_f32_16x16x32_bf16 v[6:9], v[176:179], v[232:235], v[6:9]
	v_mfma_f32_16x16x32_bf16 v[2:5], v[184:187], v[232:235], v[2:5]
	s_setprio 0
	s_add_i32 s44, s44, 2
	s_add_u32 s12, s12, 0x100
	s_addc_u32 s13, s13, 0
	s_add_u32 s42, s42, 0x100
	s_addc_u32 s43, s43, 0
	s_barrier
	s_cmp_gt_u32 s44, 13
	s_cbranch_scc0 .LBB0_637
	s_and_b64 vcc, exec, s[68:69]
	s_cbranch_vccz .LBB0_640
	s_barrier

; #define PG8_STAGE(bufoff, gbase, voff) do { _Pragma("unroll") for (int _i = 0; _i < 2; ++_i) \
;         __builtin_amdgcn_global_load_lds((const unsigned*)((const char*)(gbase) + (voff)[_i]), (LAS unsigned*)(lds + (bufoff) + ldsw + _i * 8192), 16, 0, 0); } while (0)
; #define PG8_STAGE_A(bufoff, gbase, spf) do { _Pragma("unroll") for (int _i = 0; _i < 2; ++_i) \
;         __builtin_amdgcn_global_load_lds((const unsigned*)((const char*)(gbase) + (Epi::SPECIAL_ROWS && (spf) ? voffS[_i] : voffA[_i])), (LAS unsigned*)(lds + (bufoff) + ldsw + _i * 8192), 16, 0, 0); } while (0)
; #define PG8_LDA(dst, b, h) do { _Pragma("unroll") for (int m = 0; m < 4; ++m) _Pragma("unroll") for (int k = 0; k < 2; ++k) dst[m][k] = *(const LAS bf16x8*)(lds + PG8_SA(b, h) + aoff + m * 2048 + k * 1024); } while (0)
; #define PG8_LDB(dst, b, h) do { _Pragma("unroll") for (int n = 0; n < 2; ++n) _Pragma("unroll") for (int k = 0; k < 2; ++k) dst[n][k] = *(const LAS bf16x8*)(lds + PG8_SB(b, h) + boff + n * 2048 + k * 1024); } while (0)
; #define PG8_WAIT_V(n) asm volatile("s_waitcnt vmcnt(" #n ")" ::: "memory")
; #define PG8_WAIT_L(n) asm volatile("s_waitcnt lgkmcnt(" #n ")" ::: "memory")
; #define PG8_BAR __builtin_amdgcn_s_barrier()
; #define PG8_SCHED __builtin_amdgcn_sched_barrier(0)
; template <class Epi>
; __device__ __forceinline__ void gemm_phase(LAS unsigned char* lds, const Gemm g, const Sched& S, const Epi& E) {
;     ...
;             const char* a1 = cA + (size_t)((t + 1) & kmask) * kstep;
;             const char* a2 = last ? nA : cA + (size_t)((t + 2) & kmask) * kstep; const char* b2 = last ? nB : cB + (size_t)((t + 2) & kmask) * kstep;
;             const char* a3 = a2 + kstep; const char* b3 = b2 + kstep;
;             const bool sp2 = last ? nsp : csp; const size_t hA2 = last ? nhA : chA;
;             PG8_LDB(B0, 0, 0); PG8_LDB(B1, 0, 1); PG8_SCHED; PG8_LDA(At, 0, 0); PG8_STAGE_A(PG8_SA(1, 1), a1 + chA, csp);
;             PG8_WAIT_V(8); PG8_WAIT_L(0); PG8_BAR; PG8_MMA(0, 0, At, B0); PG8_MMA(0, 1, At, B1); PG8_BAR; PG8_SCHED;
;             PG8_LDA(At, 0, 1); PG8_STAGE(PG8_SB(0, 0), b2, voffB); PG8_STAGE(PG8_SB(0, 1), b2 + hstepB, voffB); PG8_STAGE_A(PG8_SA(0, 0), a2, sp2);
;             PG8_WAIT_V(8); PG8_WAIT_L(0); PG8_BAR; PG8_MMA(1, 0, At, B0); PG8_MMA(1, 1, At, B1); PG8_BAR; PG8_SCHED;
.LBB0_1023:
	s_add_u32 s42, s34, 0x100
	s_addc_u32 s43, s35, 0
	s_add_i32 s65, 0, 0x10000
	s_cmp_eq_u32 s31, 40
	s_cselect_b32 s9, s1, s43
	s_cselect_b32 s8, s0, s42
	s_cselect_b32 s23, s19, s30
	s_cselect_b32 s22, s18, s13
	s_add_i32 s66, 0, 0x14000
	v_add_u32_e32 v142, s65, v178
	v_add_u32_e32 v166, s66, v178
	ds_read_b128 v[130:133], v142
	ds_read_b128 v[134:137], v142 offset:1024
	ds_read_b128 v[138:141], v142 offset:2048
	ds_read_b128 v[142:145], v142 offset:3072
	ds_read_b128 v[146:149], v166
	ds_read_b128 v[150:153], v166 offset:1024
	ds_read_b128 v[154:157], v166 offset:2048
	ds_read_b128 v[166:169], v166 offset:3072
	v_lshl_add_u64 v[200:201], s[34:35], 0, v[162:163]
	s_add_i32 m0, s45, 0xc000
	ds_read_b128 v[170:173], v180
	ds_read_b128 v[174:177], v180 offset:1024
	ds_read_b128 v[182:185], v180 offset:2048
	ds_read_b128 v[186:189], v180 offset:3072
	ds_read_b128 v[190:193], v180 offset:4096
	ds_read_b128 v[208:211], v180 offset:5120
	ds_read_b128 v[212:215], v180 offset:6144
	ds_read_b128 v[216:219], v180 offset:7168
	global_load_lds_dwordx4 v[200:201], off
	v_lshl_add_u64 v[200:201], s[34:35], 0, v[164:165]
	s_add_i32 m0, s45, 0xe000
	s_nop 0
	global_load_lds_dwordx4 v[200:201], off
	s_waitcnt vmcnt(8)
	s_waitcnt lgkmcnt(0)
	s_barrier
	s_setprio 1
	s_waitcnt lgkmcnt(0)
	v_mfma_f32_16x16x32_bf16 v[126:129], v[130:133], v[170:173], v[126:129]
	v_mfma_f32_16x16x32_bf16 v[122:125], v[138:141], v[170:173], v[122:125]
	v_mfma_f32_16x16x32_bf16 v[110:113], v[130:133], v[182:185], v[110:113]
	v_mfma_f32_16x16x32_bf16 v[106:109], v[138:141], v[182:185], v[106:109]
	v_mfma_f32_16x16x32_bf16 v[94:97], v[130:133], v[190:193], v[94:97]
	v_mfma_f32_16x16x32_bf16 v[90:93], v[138:141], v[190:193], v[90:93]
	v_mfma_f32_16x16x32_bf16 v[78:81], v[130:133], v[212:215], v[78:81]
	v_mfma_f32_16x16x32_bf16 v[74:77], v[138:141], v[212:215], v[74:77]
	v_mfma_f32_16x16x32_bf16 v[126:129], v[134:137], v[174:177], v[126:129]
	v_mfma_f32_16x16x32_bf16 v[122:125], v[142:145], v[174:177], v[122:125]
	v_mfma_f32_16x16x32_bf16 v[110:113], v[134:137], v[186:189], v[110:113]
	v_mfma_f32_16x16x32_bf16 v[106:109], v[142:145], v[186:189], v[106:109]
	v_mfma_f32_16x16x32_bf16 v[94:97], v[134:137], v[208:211], v[94:97]
	v_mfma_f32_16x16x32_bf16 v[90:93], v[142:145], v[208:211], v[90:93]
	v_mfma_f32_16x16x32_bf16 v[78:81], v[134:137], v[216:219], v[78:81]
	v_mfma_f32_16x16x32_bf16 v[74:77], v[142:145], v[216:219], v[74:77]
	s_setprio 0
	s_setprio 1
	v_mfma_f32_16x16x32_bf16 v[118:121], v[146:149], v[170:173], v[118:121]
	v_mfma_f32_16x16x32_bf16 v[114:117], v[154:157], v[170:173], v[114:117]
	v_mfma_f32_16x16x32_bf16 v[102:105], v[146:149], v[182:185], v[102:105]
	v_mfma_f32_16x16x32_bf16 v[98:101], v[154:157], v[182:185], v[98:101]
	v_mfma_f32_16x16x32_bf16 v[86:89], v[146:149], v[190:193], v[86:89]
	v_mfma_f32_16x16x32_bf16 v[82:85], v[154:157], v[190:193], v[82:85]
	v_mfma_f32_16x16x32_bf16 v[70:73], v[146:149], v[212:215], v[70:73]
	v_mfma_f32_16x16x32_bf16 v[66:69], v[154:157], v[212:215], v[66:69]
	v_mfma_f32_16x16x32_bf16 v[118:121], v[150:153], v[174:177], v[118:121]
	v_mfma_f32_16x16x32_bf16 v[114:117], v[166:169], v[174:177], v[114:117]
	v_mfma_f32_16x16x32_bf16 v[102:105], v[150:153], v[186:189], v[102:105]
	v_mfma_f32_16x16x32_bf16 v[98:101], v[166:169], v[186:189], v[98:101]
	v_mfma_f32_16x16x32_bf16 v[86:89], v[150:153], v[208:211], v[86:89]
	v_mfma_f32_16x16x32_bf16 v[82:85], v[166:169], v[208:211], v[82:85]
	v_mfma_f32_16x16x32_bf16 v[70:73], v[150:153], v[216:219], v[70:73]
	v_mfma_f32_16x16x32_bf16 v[66:69], v[166:169], v[216:219], v[66:69]
	s_setprio 0
	s_barrier
	s_add_i32 s34, s65, s44
	v_lshl_add_u64 v[200:201], s[22:23], 0, v[0:1]
	s_mov_b32 m0, s34
	ds_read_b128 v[170:173], v180 offset:16384
	ds_read_b128 v[174:177], v180 offset:17408
	ds_read_b128 v[182:185], v180 offset:18432
	ds_read_b128 v[186:189], v180 offset:19456
	ds_read_b128 v[190:193], v180 offset:20480
	ds_read_b128 v[208:211], v180 offset:21504
	ds_read_b128 v[212:215], v180 offset:22528
	ds_read_b128 v[216:219], v180 offset:23552
	global_load_lds_dwordx4 v[200:201], off
	s_add_i32 m0, s34, 0x2000
	s_add_u32 s34, s22, 0xb0000
	v_lshl_add_u64 v[202:203], s[22:23], 0, v[158:159]
	s_addc_u32 s35, s23, 0
	s_add_i32 s65, s66, s44
	global_load_lds_dwordx4 v[202:203], off
	v_lshl_add_u64 v[204:205], s[34:35], 0, v[0:1]
	s_mov_b32 m0, s65
	v_lshl_add_u64 v[206:207], s[8:9], 0, v[158:159]
	global_load_lds_dwordx4 v[204:205], off
	v_lshl_add_u64 v[204:205], s[34:35], 0, v[158:159]
	s_add_i32 m0, s65, 0x2000
	s_nop 0
	global_load_lds_dwordx4 v[204:205], off
	v_lshl_add_u64 v[204:205], s[8:9], 0, v[0:1]
	s_mov_b32 m0, s45
	s_nop 0
	global_load_lds_dwordx4 v[204:205], off
	s_mov_b32 m0, s46
	s_nop 0
	global_load_lds_dwordx4 v[206:207], off
	s_waitcnt vmcnt(8)
	s_waitcnt lgkmcnt(0)
	s_barrier
; #define PG8_STAGE_A(bufoff, gbase, spf) do { _Pragma("unroll") for (int _i = 0; _i < 2; ++_i) \
;         __builtin_amdgcn_global_load_lds((const unsigned*)((const char*)(gbase) + (Epi::SPECIAL_ROWS && (spf) ? voffS[_i] : voffA[_i])), (LAS unsigned*)(lds + (bufoff) + ldsw + _i * 8192), 16, 0, 0); } while (0)
; #define PG8_LDA(dst, b, h) do { _Pragma("unroll") for (int m = 0; m < 4; ++m) _Pragma("unroll") for (int k = 0; k < 2; ++k) dst[m][k] = *(const LAS bf16x8*)(lds + PG8_SA(b, h) + aoff + m * 2048 + k * 1024); } while (0)
; #define PG8_LDB(dst, b, h) do { _Pragma("unroll") for (int n = 0; n < 2; ++n) _Pragma("unroll") for (int k = 0; k < 2; ++k) dst[n][k] = *(const LAS bf16x8*)(lds + PG8_SB(b, h) + boff + n * 2048 + k * 1024); } while (0)
; #define PG8_MMA(ai, bj, At, Bt) do { __builtin_amdgcn_s_setprio(1); _Pragma("unroll") for (int m = 0; m < 4; ++m) _Pragma("unroll") for (int n = 0; n < 2; ++n) _Pragma("unroll") for (int k = 0; k < 2; ++k) \
;         acc[ai][bj][m][n] = __builtin_amdgcn_mfma_f32_16x16x32_bf16(Bt[n][k], At[m][k], acc[ai][bj][m][n], 0, 0, 0); __builtin_amdgcn_s_setprio(0); } while (0)
; #define PG8_WAIT_V(n) asm volatile("s_waitcnt vmcnt(" #n ")" ::: "memory")
; #define PG8_WAIT_L(n) asm volatile("s_waitcnt lgkmcnt(" #n ")" ::: "memory")
; #define PG8_BAR __builtin_amdgcn_s_barrier()
; #define PG8_SCHED __builtin_amdgcn_sched_barrier(0)
; template <class Epi>
; __device__ __forceinline__ void gemm_phase(LAS unsigned char* lds, const Gemm g, const Sched& S, const Epi& E) {
;     ...
;             PG8_WAIT_V(8); PG8_WAIT_L(0); PG8_BAR; PG8_MMA(1, 0, At, B0); PG8_MMA(1, 1, At, B1); PG8_BAR; PG8_SCHED;
;             PG8_LDB(B0, 1, 0); PG8_LDB(B1, 1, 1); PG8_SCHED; PG8_LDA(At, 1, 0); PG8_STAGE_A(PG8_SA(0, 1), a2 + hA2, sp2);
;             PG8_WAIT_V(8); PG8_WAIT_L(0); PG8_BAR; PG8_MMA(0, 0, At, B0); PG8_MMA(0, 1, At, B1); PG8_BAR; PG8_SCHED;
	s_setprio 1
	s_waitcnt lgkmcnt(0)
	v_mfma_f32_16x16x32_bf16 v[62:65], v[130:133], v[170:173], v[62:65]
	v_mfma_f32_16x16x32_bf16 v[58:61], v[138:141], v[170:173], v[58:61]
	v_mfma_f32_16x16x32_bf16 v[46:49], v[130:133], v[182:185], v[46:49]
	v_mfma_f32_16x16x32_bf16 v[42:45], v[138:141], v[182:185], v[42:45]
	v_mfma_f32_16x16x32_bf16 v[30:33], v[130:133], v[190:193], v[30:33]
	v_mfma_f32_16x16x32_bf16 v[26:29], v[138:141], v[190:193], v[26:29]
	v_mfma_f32_16x16x32_bf16 v[14:17], v[130:133], v[212:215], v[14:17]
	v_mfma_f32_16x16x32_bf16 v[10:13], v[138:141], v[212:215], v[10:13]
	v_mfma_f32_16x16x32_bf16 v[62:65], v[134:137], v[174:177], v[62:65]
	v_mfma_f32_16x16x32_bf16 v[58:61], v[142:145], v[174:177], v[58:61]
	v_mfma_f32_16x16x32_bf16 v[46:49], v[134:137], v[186:189], v[46:49]
	v_mfma_f32_16x16x32_bf16 v[42:45], v[142:145], v[186:189], v[42:45]
	v_mfma_f32_16x16x32_bf16 v[30:33], v[134:137], v[208:211], v[30:33]
	v_mfma_f32_16x16x32_bf16 v[26:29], v[142:145], v[208:211], v[26:29]
	v_mfma_f32_16x16x32_bf16 v[14:17], v[134:137], v[216:219], v[14:17]
	v_mfma_f32_16x16x32_bf16 v[10:13], v[142:145], v[216:219], v[10:13]
	s_setprio 0
	s_setprio 1
	v_mfma_f32_16x16x32_bf16 v[54:57], v[146:149], v[170:173], v[54:57]
	v_mfma_f32_16x16x32_bf16 v[50:53], v[154:157], v[170:173], v[50:53]
	v_mfma_f32_16x16x32_bf16 v[38:41], v[146:149], v[182:185], v[38:41]
	v_mfma_f32_16x16x32_bf16 v[34:37], v[154:157], v[182:185], v[34:37]
	v_mfma_f32_16x16x32_bf16 v[22:25], v[146:149], v[190:193], v[22:25]
	v_mfma_f32_16x16x32_bf16 v[18:21], v[154:157], v[190:193], v[18:21]
	v_mfma_f32_16x16x32_bf16 v[6:9], v[146:149], v[212:215], v[6:9]
	v_mfma_f32_16x16x32_bf16 v[2:5], v[154:157], v[212:215], v[2:5]
	v_mfma_f32_16x16x32_bf16 v[54:57], v[150:153], v[174:177], v[54:57]
	v_mfma_f32_16x16x32_bf16 v[50:53], v[166:169], v[174:177], v[50:53]
	v_mfma_f32_16x16x32_bf16 v[38:41], v[150:153], v[186:189], v[38:41]
	v_mfma_f32_16x16x32_bf16 v[34:37], v[166:169], v[186:189], v[34:37]
	v_mfma_f32_16x16x32_bf16 v[22:25], v[150:153], v[208:211], v[22:25]
	v_mfma_f32_16x16x32_bf16 v[18:21], v[166:169], v[208:211], v[18:21]
	v_mfma_f32_16x16x32_bf16 v[6:9], v[150:153], v[216:219], v[6:9]
	v_mfma_f32_16x16x32_bf16 v[2:5], v[166:169], v[216:219], v[2:5]
	s_setprio 0
	s_barrier
	s_add_i32 s34, 0, 0x18000
	s_add_i32 s35, 0, 0x1c000
	v_add_u32_e32 v142, s34, v178
	v_add_u32_e32 v166, s35, v178
	ds_read_b128 v[130:133], v142
	ds_read_b128 v[134:137], v142 offset:1024
	ds_read_b128 v[138:141], v142 offset:2048
	ds_read_b128 v[142:145], v142 offset:3072
	ds_read_b128 v[146:149], v166
	ds_read_b128 v[150:153], v166 offset:1024
	ds_read_b128 v[154:157], v166 offset:2048
	ds_read_b128 v[166:169], v166 offset:3072
	s_add_u32 s8, s8, 0xb0000
	s_addc_u32 s9, s9, 0
	s_mov_b32 m0, s47
	v_lshl_add_u64 v[220:221], s[8:9], 0, v[0:1]
	ds_read_b128 v[170:173], v180 offset:32768
	ds_read_b128 v[174:177], v180 offset:33792
	ds_read_b128 v[182:185], v180 offset:34816
	ds_read_b128 v[186:189], v180 offset:35840
	ds_read_b128 v[190:193], v180 offset:36864
	ds_read_b128 v[208:211], v180 offset:37888
	ds_read_b128 v[212:215], v180 offset:38912
	ds_read_b128 v[216:219], v180 offset:39936
	global_load_lds_dwordx4 v[220:221], off
	v_lshl_add_u64 v[220:221], s[8:9], 0, v[158:159]
	s_mov_b32 m0, s54
	s_nop 0
	global_load_lds_dwordx4 v[220:221], off
	s_waitcnt vmcnt(8)
	s_waitcnt lgkmcnt(0)
	s_barrier
	s_setprio 1
	s_waitcnt lgkmcnt(0)
	v_mfma_f32_16x16x32_bf16 v[126:129], v[130:133], v[170:173], v[126:129]
	v_mfma_f32_16x16x32_bf16 v[122:125], v[138:141], v[170:173], v[122:125]
	v_mfma_f32_16x16x32_bf16 v[110:113], v[130:133], v[182:185], v[110:113]
	v_mfma_f32_16x16x32_bf16 v[106:109], v[138:141], v[182:185], v[106:109]
	v_mfma_f32_16x16x32_bf16 v[94:97], v[130:133], v[190:193], v[94:97]
	v_mfma_f32_16x16x32_bf16 v[90:93], v[138:141], v[190:193], v[90:93]
	v_mfma_f32_16x16x32_bf16 v[78:81], v[130:133], v[212:215], v[78:81]
	v_mfma_f32_16x16x32_bf16 v[74:77], v[138:141], v[212:215], v[74:77]
	v_mfma_f32_16x16x32_bf16 v[126:129], v[134:137], v[174:177], v[126:129]
	v_mfma_f32_16x16x32_bf16 v[122:125], v[142:145], v[174:177], v[122:125]
	v_mfma_f32_16x16x32_bf16 v[110:113], v[134:137], v[186:189], v[110:113]
	v_mfma_f32_16x16x32_bf16 v[106:109], v[142:145], v[186:189], v[106:109]
	v_mfma_f32_16x16x32_bf16 v[94:97], v[134:137], v[208:211], v[94:97]
	v_mfma_f32_16x16x32_bf16 v[90:93], v[142:145], v[208:211], v[90:93]
	v_mfma_f32_16x16x32_bf16 v[78:81], v[134:137], v[216:219], v[78:81]
	v_mfma_f32_16x16x32_bf16 v[74:77], v[142:145], v[216:219], v[74:77]
	s_setprio 0
	s_setprio 1
	v_mfma_f32_16x16x32_bf16 v[118:121], v[146:149], v[170:173], v[118:121]
	v_mfma_f32_16x16x32_bf16 v[114:117], v[154:157], v[170:173], v[114:117]
	v_mfma_f32_16x16x32_bf16 v[102:105], v[146:149], v[182:185], v[102:105]
	v_mfma_f32_16x16x32_bf16 v[98:101], v[154:157], v[182:185], v[98:101]
	v_mfma_f32_16x16x32_bf16 v[86:89], v[146:149], v[190:193], v[86:89]
	v_mfma_f32_16x16x32_bf16 v[82:85], v[154:157], v[190:193], v[82:85]
	v_mfma_f32_16x16x32_bf16 v[70:73], v[146:149], v[212:215], v[70:73]
	v_mfma_f32_16x16x32_bf16 v[66:69], v[154:157], v[212:215], v[66:69]
	v_mfma_f32_16x16x32_bf16 v[118:121], v[150:153], v[174:177], v[118:121]
	v_mfma_f32_16x16x32_bf16 v[114:117], v[166:169], v[174:177], v[114:117]
	v_mfma_f32_16x16x32_bf16 v[102:105], v[150:153], v[186:189], v[102:105]
	v_mfma_f32_16x16x32_bf16 v[98:101], v[166:169], v[186:189], v[98:101]
	v_mfma_f32_16x16x32_bf16 v[86:89], v[150:153], v[208:211], v[86:89]
	v_mfma_f32_16x16x32_bf16 v[82:85], v[166:169], v[208:211], v[82:85]
	v_mfma_f32_16x16x32_bf16 v[70:73], v[150:153], v[216:219], v[70:73]
	v_mfma_f32_16x16x32_bf16 v[66:69], v[166:169], v[216:219], v[66:69]
	s_setprio 0
	s_barrier
; #define PG8_STAGE(bufoff, gbase, voff) do { _Pragma("unroll") for (int _i = 0; _i < 2; ++_i) \
;         __builtin_amdgcn_global_load_lds((const unsigned*)((const char*)(gbase) + (voff)[_i]), (LAS unsigned*)(lds + (bufoff) + ldsw + _i * 8192), 16, 0, 0); } while (0)
; #define PG8_STAGE_A(bufoff, gbase, spf) do { _Pragma("unroll") for (int _i = 0; _i < 2; ++_i) \
;         __builtin_amdgcn_global_load_lds((const unsigned*)((const char*)(gbase) + (Epi::SPECIAL_ROWS && (spf) ? voffS[_i] : voffA[_i])), (LAS unsigned*)(lds + (bufoff) + ldsw + _i * 8192), 16, 0, 0); } while (0)
; #define PG8_LDA(dst, b, h) do { _Pragma("unroll") for (int m = 0; m < 4; ++m) _Pragma("unroll") for (int k = 0; k < 2; ++k) dst[m][k] = *(const LAS bf16x8*)(lds + PG8_SA(b, h) + aoff + m * 2048 + k * 1024); } while (0)
; #define PG8_MMA(ai, bj, At, Bt) do { __builtin_amdgcn_s_setprio(1); _Pragma("unroll") for (int m = 0; m < 4; ++m) _Pragma("unroll") for (int n = 0; n < 2; ++n) _Pragma("unroll") for (int k = 0; k < 2; ++k) \
;         acc[ai][bj][m][n] = __builtin_amdgcn_mfma_f32_16x16x32_bf16(Bt[n][k], At[m][k], acc[ai][bj][m][n], 0, 0, 0); __builtin_amdgcn_s_setprio(0); } while (0)
; #define PG8_WAIT_V(n) asm volatile("s_waitcnt vmcnt(" #n ")" ::: "memory")
; #define PG8_WAIT_L(n) asm volatile("s_waitcnt lgkmcnt(" #n ")" ::: "memory")
; #define PG8_BAR __builtin_amdgcn_s_barrier()
; #define PG8_SCHED __builtin_amdgcn_sched_barrier(0)
; template <class Epi>
; __device__ __forceinline__ void gemm_phase(LAS unsigned char* lds, const Gemm g, const Sched& S, const Epi& E) {
;     ...
;             PG8_LDA(At, 1, 1); PG8_STAGE(PG8_SB(1, 0), b3, voffB); PG8_STAGE(PG8_SB(1, 1), b3 + hstepB, voffB); PG8_STAGE_A(PG8_SA(1, 0), a3, sp2);
;             PG8_WAIT_V(8); PG8_WAIT_L(0); PG8_BAR; PG8_MMA(1, 0, At, B0); PG8_MMA(1, 1, At, B1); PG8_BAR; PG8_SCHED;
;         }
;         if (wr == 0) PG8_BAR;
	s_add_i32 s8, s34, s44
	v_lshl_add_u64 v[200:201], v[200:201], 0, s[20:21]
	s_mov_b32 m0, s8
	ds_read_b128 v[170:173], v180 offset:49152
	ds_read_b128 v[174:177], v180 offset:50176
	ds_read_b128 v[182:185], v180 offset:51200
	ds_read_b128 v[186:189], v180 offset:52224
	ds_read_b128 v[190:193], v180 offset:53248
	ds_read_b128 v[208:211], v180 offset:54272
	ds_read_b128 v[212:215], v180 offset:55296
	ds_read_b128 v[216:219], v180 offset:56320
	global_load_lds_dwordx4 v[200:201], off
	s_add_i32 m0, s8, 0x2000
	s_add_u32 s8, s22, 0xb0080
	v_lshl_add_u64 v[200:201], v[202:203], 0, s[20:21]
	s_addc_u32 s9, s23, 0
	s_add_i32 s22, s35, s44
	global_load_lds_dwordx4 v[200:201], off
	v_lshl_add_u64 v[200:201], s[8:9], 0, v[0:1]
	s_mov_b32 m0, s22
	s_nop 0
	global_load_lds_dwordx4 v[200:201], off
	v_lshl_add_u64 v[200:201], s[8:9], 0, v[158:159]
	s_add_i32 m0, s22, 0x2000
	s_nop 0
	global_load_lds_dwordx4 v[200:201], off
	v_lshl_add_u64 v[200:201], v[204:205], 0, s[20:21]
	s_mov_b32 m0, s56
	s_nop 0
	global_load_lds_dwordx4 v[200:201], off
	v_lshl_add_u64 v[200:201], v[206:207], 0, s[20:21]
	s_mov_b32 m0, s57
	s_nop 0
	global_load_lds_dwordx4 v[200:201], off
	s_waitcnt vmcnt(8)
	s_waitcnt lgkmcnt(0)
	s_barrier
	s_setprio 1
	s_waitcnt lgkmcnt(0)
	v_mfma_f32_16x16x32_bf16 v[62:65], v[130:133], v[170:173], v[62:65]
	v_mfma_f32_16x16x32_bf16 v[58:61], v[138:141], v[170:173], v[58:61]
	v_mfma_f32_16x16x32_bf16 v[46:49], v[130:133], v[182:185], v[46:49]
	v_mfma_f32_16x16x32_bf16 v[42:45], v[138:141], v[182:185], v[42:45]
	v_mfma_f32_16x16x32_bf16 v[30:33], v[130:133], v[190:193], v[30:33]
	v_mfma_f32_16x16x32_bf16 v[26:29], v[138:141], v[190:193], v[26:29]
	v_mfma_f32_16x16x32_bf16 v[14:17], v[130:133], v[212:215], v[14:17]
	v_mfma_f32_16x16x32_bf16 v[10:13], v[138:141], v[212:215], v[10:13]
	v_mfma_f32_16x16x32_bf16 v[62:65], v[134:137], v[174:177], v[62:65]
	v_mfma_f32_16x16x32_bf16 v[58:61], v[142:145], v[174:177], v[58:61]
	v_mfma_f32_16x16x32_bf16 v[46:49], v[134:137], v[186:189], v[46:49]
	v_mfma_f32_16x16x32_bf16 v[42:45], v[142:145], v[186:189], v[42:45]
	v_mfma_f32_16x16x32_bf16 v[30:33], v[134:137], v[208:211], v[30:33]
	v_mfma_f32_16x16x32_bf16 v[26:29], v[142:145], v[208:211], v[26:29]
	v_mfma_f32_16x16x32_bf16 v[14:17], v[134:137], v[216:219], v[14:17]
	v_mfma_f32_16x16x32_bf16 v[10:13], v[142:145], v[216:219], v[10:13]
	s_setprio 0
	s_setprio 1
	v_mfma_f32_16x16x32_bf16 v[54:57], v[146:149], v[170:173], v[54:57]
	v_mfma_f32_16x16x32_bf16 v[50:53], v[154:157], v[170:173], v[50:53]
	v_mfma_f32_16x16x32_bf16 v[38:41], v[146:149], v[182:185], v[38:41]
	v_mfma_f32_16x16x32_bf16 v[34:37], v[154:157], v[182:185], v[34:37]
	v_mfma_f32_16x16x32_bf16 v[22:25], v[146:149], v[190:193], v[22:25]
	v_mfma_f32_16x16x32_bf16 v[18:21], v[154:157], v[190:193], v[18:21]
	v_mfma_f32_16x16x32_bf16 v[6:9], v[146:149], v[212:215], v[6:9]
	v_mfma_f32_16x16x32_bf16 v[2:5], v[154:157], v[212:215], v[2:5]
	v_mfma_f32_16x16x32_bf16 v[54:57], v[150:153], v[174:177], v[54:57]
	v_mfma_f32_16x16x32_bf16 v[50:53], v[166:169], v[174:177], v[50:53]
	v_mfma_f32_16x16x32_bf16 v[38:41], v[150:153], v[186:189], v[38:41]
	v_mfma_f32_16x16x32_bf16 v[34:37], v[166:169], v[186:189], v[34:37]
	v_mfma_f32_16x16x32_bf16 v[22:25], v[150:153], v[208:211], v[22:25]
	v_mfma_f32_16x16x32_bf16 v[18:21], v[166:169], v[208:211], v[18:21]
	v_mfma_f32_16x16x32_bf16 v[6:9], v[150:153], v[216:219], v[6:9]
	v_mfma_f32_16x16x32_bf16 v[2:5], v[166:169], v[216:219], v[2:5]
	s_setprio 0
	s_add_i32 s31, s31, 2
	s_add_u32 s13, s13, 0x100
	s_addc_u32 s30, s30, 0
	s_barrier
	s_cmp_gt_u32 s31, 41
	s_mov_b64 s[34:35], s[42:43]
	s_cbranch_scc0 .LBB0_1023
	s_and_b64 vcc, exec, s[14:15]
	s_cbranch_vccz .LBB0_1026
	s_barrier
